# v38 stack plus nt cache policy on the weight-tile LDS-DMA loads of the four sample-row skinny GEMMs (weights streamed once per phase)
# speedup vs baseline: 1.0246x; 1.0246x over previous
.LBB0_146:
	s_mov_b64 s[4:5], s[0:1]
	s_load_dwordx2 s[4:5], s[4:5], 0xa0
	s_mov_b64 s[6:7], s[0:1]
	v_mov_b32_e32 v45, v0
	s_load_dwordx2 s[6:7], s[6:7], 0xa0
	s_waitcnt lgkmcnt(0)
	s_add_u32 s46, s4, 0x1c400000
	s_addc_u32 s47, s5, 0
	v_readfirstlane_b32 s8, v45
	s_ashr_i32 s48, s8, 6
	s_lshl_b32 s44, s48, 5
	v_bfe_u32 v2, v45, 3, 3
	v_or_b32_e32 v3, s44, v2
	v_lshlrev_b32_e32 v4, 4, v45
	v_lshlrev_b32_e32 v3, 13, v3
	v_and_b32_e32 v5, 48, v45
	v_and_b32_e32 v4, 0x70, v4
	v_bitop3_b32 v34, v3, v4, v5 bitop3:0xf6
	v_or_b32_e32 v3, 8, v2
	s_ashr_i32 s8, s43, 2
	v_or_b32_e32 v4, s44, v3
	v_lshrrev_b32_e32 v3, 1, v3
	s_ashr_i32 s9, s8, 31
	v_xor_b32_e32 v3, v3, v45
	s_lshl_b64 s[8:9], s[8:9], 21
	v_lshlrev_b32_e32 v4, 13, v4
	v_lshlrev_b32_e32 v3, 4, v3
	s_add_u32 s6, s6, s8
	v_and_or_b32 v36, v3, s33, v4
	v_or_b32_e32 v3, 24, v2
	s_addc_u32 s7, s7, s9
	s_lshl_b32 s8, s43, 13
	v_or_b32_e32 v4, s44, v3
	v_lshrrev_b32_e32 v3, 1, v3
	s_and_b32 s8, s8, 0x6000
	v_xor_b32_e32 v3, v3, v45
	s_add_u32 s6, s6, s8
	v_lshlrev_b32_e32 v4, 13, v4
	v_lshlrev_b32_e32 v3, 4, v3
	v_lshl_or_b32 v2, s48, 3, v2
	s_addc_u32 s7, s7, 0
	s_lshl_b32 s8, s48, 12
	v_and_or_b32 v40, v3, s33, v4
	v_lshlrev_b32_e32 v3, 7, v2
	v_lshrrev_b32_e32 v2, 1, v2
	s_add_i32 s9, s8, 0
	v_xor_b32_e32 v2, v2, v45
	v_lshl_add_u64 v[4:5], s[46:47], 0, v[34:35]
	s_mov_b32 s45, m0
	s_mov_b32 m0, s9
	s_nop 0
	global_load_lds_dwordx4 v[4:5], off
	s_mov_b32 m0, s45
	v_mov_b32_e32 v37, v35
	s_or_b32 s9, s8, 0x400
	v_or_b32_e32 v38, 0x20000, v34
	v_lshlrev_b32_e32 v2, 4, v2
	v_lshl_add_u64 v[4:5], s[46:47], 0, v[36:37]
	s_add_i32 s45, s9, 0
	v_mov_b32_e32 v39, v35
	v_and_or_b32 v2, v2, s33, v3
	s_mov_b32 s49, m0
	s_mov_b32 m0, s45
	s_nop 0
	global_load_lds_dwordx4 v[4:5], off
	s_mov_b32 m0, s49
	v_lshl_add_u64 v[4:5], s[46:47], 0, v[38:39]
	s_or_b32 s45, s8, 0x800
	v_mov_b32_e32 v41, v35
	v_mov_b32_e32 v3, v35
	s_add_i32 s49, s45, 0
	s_mov_b32 s50, m0
	s_mov_b32 m0, s49
	s_nop 0
	global_load_lds_dwordx4 v[4:5], off
	s_mov_b32 m0, s50
	v_lshl_add_u64 v[4:5], s[46:47], 0, v[40:41]
	s_or_b32 s46, s8, 0xc00
	v_lshl_add_u64 v[2:3], s[6:7], 0, v[2:3]
	s_lshl_b32 s6, s48, 10
	s_add_i32 s47, s46, 0
	s_add_i32 s48, s6, 0
	s_mov_b32 s49, m0
	s_mov_b32 m0, s47
	s_nop 0
	global_load_lds_dwordx4 v[4:5], off
	s_mov_b32 m0, s49
	s_add_i32 s47, s6, 0x8000
	s_add_i32 s6, s48, 0x8000
	v_lshl_add_u64 v[4:5], v[2:3], 0, s[14:15]
	s_mov_b32 s7, m0
	s_mov_b32 m0, s6
	s_nop 0
	global_load_lds_dwordx4 v[4:5], off nt
	s_mov_b32 m0, s7
	s_add_u32 s6, s4, 0x1c400080
	s_addc_u32 s7, s5, 0
	v_lshl_add_u64 v[4:5], s[6:7], 0, v[34:35]
	s_add_i32 s49, s8, s40
	s_mov_b32 s50, m0
	s_mov_b32 m0, s49
	s_nop 0
	global_load_lds_dwordx4 v[4:5], off
	s_mov_b32 m0, s50
	v_lshl_add_u64 v[4:5], s[6:7], 0, v[36:37]
	s_add_i32 s49, s9, s40
	s_mov_b32 s50, m0
	s_mov_b32 m0, s49
	s_nop 0
	global_load_lds_dwordx4 v[4:5], off
	s_mov_b32 m0, s50
	v_lshl_add_u64 v[4:5], s[6:7], 0, v[38:39]
	s_add_i32 s49, s45, s40
	s_mov_b32 s50, m0
	s_mov_b32 m0, s49
	s_nop 0
	global_load_lds_dwordx4 v[4:5], off
	s_mov_b32 m0, s50
	v_lshl_add_u64 v[4:5], s[6:7], 0, v[40:41]
	v_bfe_u32 v46, v45, 5, 1
	v_lshrrev_b32_e32 v7, 1, v45
	s_add_i32 s6, s46, s40
	s_mov_b32 s7, m0
	s_mov_b32 m0, s6
	s_nop 0
	global_load_lds_dwordx4 v[4:5], off
	s_mov_b32 m0, s7
	v_lshl_add_u64 v[4:5], v[2:3], 0, s[16:17]
	v_bfe_u32 v8, v45, 1, 3
	s_add_i32 s48, s48, 0x12000
	s_mov_b32 s6, m0
	s_mov_b32 m0, s48
	s_nop 0
	global_load_lds_dwordx4 v[4:5], off nt
	s_mov_b32 m0, s6
	v_bitop3_b32 v4, v46, v7, 7 bitop3:0x78
	v_lshlrev_b32_e32 v51, 4, v4
	v_bitop3_b32 v4, v46, v8, 2 bitop3:0x36
	v_and_b32_e32 v44, 31, v45
	v_lshlrev_b32_e32 v49, 4, v4
	v_bitop3_b32 v4, v46, v8, 4 bitop3:0x36
	v_or_b32_e32 v6, s44, v44
	v_lshlrev_b32_e32 v48, 4, v4
	v_bitop3_b32 v4, v46, v8, 6 bitop3:0x36
	v_lshlrev_b32_e32 v52, 7, v6
	v_lshlrev_b32_e32 v50, 7, v44
	v_lshlrev_b32_e32 v47, 4, v4
	v_lshl_add_u64 v[42:43], v[2:3], 0, s[18:19]
	s_mov_b64 s[6:7], 0
	s_mov_b32 s49, 0
	s_mov_b32 s48, 2
	v_mov_b32_e32 v2, v35
	v_mov_b32_e32 v3, v35
	v_mov_b32_e32 v4, v35
	v_mov_b32_e32 v5, v35
	v_mov_b32_e32 v6, v35
	v_mov_b32_e32 v7, v35
	v_mov_b32_e32 v8, v35
	v_mov_b32_e32 v9, v35
	v_mov_b32_e32 v10, v35
	v_mov_b32_e32 v11, v35
	v_mov_b32_e32 v12, v35
	v_mov_b32_e32 v13, v35
	v_mov_b32_e32 v14, v35
	v_mov_b32_e32 v15, v35
	v_mov_b32_e32 v16, v35
	v_mov_b32_e32 v17, v35
	v_mov_b32_e32 v18, v35
	v_mov_b32_e32 v19, v35
	v_mov_b32_e32 v20, v35
	v_mov_b32_e32 v21, v35
	v_mov_b32_e32 v22, v35
	v_mov_b32_e32 v23, v35
	v_mov_b32_e32 v24, v35
	v_mov_b32_e32 v25, v35
	v_mov_b32_e32 v26, v35
	v_mov_b32_e32 v27, v35
	v_mov_b32_e32 v28, v35
	v_mov_b32_e32 v29, v35
	v_mov_b32_e32 v30, v35
	v_mov_b32_e32 v31, v35
	v_mov_b32_e32 v32, v35
	v_mov_b32_e32 v33, v35
.LBB0_147:
	s_mul_i32 s50, s48, 0xa000
	s_add_i32 s73, s50, 0
	s_add_u32 s74, s4, s6
	s_addc_u32 s75, s5, s7
	s_waitcnt vmcnt(5)
	s_mul_i32 s72, s49, 0xa000
	s_add_u32 s50, s74, 0x1c400100
	s_waitcnt lgkmcnt(0)
	s_barrier
	s_addc_u32 s51, s75, 0
	s_add_i32 s76, s73, s8
	s_add_i32 s77, s73, s9
	s_add_i32 s78, s73, s45
	s_add_i32 s79, s73, s46
	s_add_i32 s73, s47, s73
	s_add_i32 s72, s72, 0
	s_add_i32 s80, s49, 1
	v_lshl_add_u64 v[56:57], s[50:51], 0, v[34:35]
	s_cmp_lg_u32 s49, 2
	s_mov_b32 s49, m0
	s_mov_b32 m0, s76
	s_nop 0
	global_load_lds_dwordx4 v[56:57], off
	s_mov_b32 m0, s49
	v_lshl_add_u64 v[58:59], s[50:51], 0, v[36:37]
	s_mov_b32 s49, m0
	s_mov_b32 m0, s77
	s_nop 0
	global_load_lds_dwordx4 v[58:59], off
	s_mov_b32 m0, s49
	v_lshl_add_u64 v[60:61], s[50:51], 0, v[38:39]
	s_mov_b32 s49, m0
	s_mov_b32 m0, s78
	s_nop 0
	global_load_lds_dwordx4 v[60:61], off
	s_mov_b32 m0, s49
	v_lshl_add_u64 v[62:63], s[50:51], 0, v[40:41]
	v_add_u32_e32 v53, s72, v52
	s_mov_b32 s49, m0
	s_mov_b32 m0, s79
	s_nop 0
	global_load_lds_dwordx4 v[62:63], off
	s_mov_b32 m0, s49
	v_lshl_add_u64 v[54:55], v[42:43], 0, s[20:21]
	v_add_u32_e32 v66, s72, v50
	v_add_u32_e32 v56, v53, v51
	s_mov_b32 s49, m0
	s_mov_b32 m0, s73
	s_nop 0
	global_load_lds_dwordx4 v[54:55], off nt
	s_mov_b32 m0, s49
	v_add_u32_e32 v64, v66, v51
	ds_read_b128 v[54:57], v56
	ds_read_b128 v[58:61], v64 offset:32768
	v_add_u32_e32 v65, v53, v49
	s_waitcnt lgkmcnt(0)
	v_mfma_f32_32x32x16_bf16 v[2:17], v[54:57], v[58:61], v[2:17]
	ds_read_b128 v[58:61], v64 offset:36864
	ds_read_b128 v[62:65], v65
	v_add_u32_e32 v67, v66, v49
	v_add_u32_e32 v68, v53, v48
	v_add_u32_e32 v69, v66, v48
	v_add_u32_e32 v74, v66, v47
	v_add_u32_e32 v53, v53, v47
	s_cselect_b32 s50, s80, 0
	s_waitcnt lgkmcnt(0)
	v_mfma_f32_32x32x16_bf16 v[18:33], v[54:57], v[58:61], v[18:33]
	ds_read_b128 v[54:57], v67 offset:32768
	ds_read_b128 v[58:61], v67 offset:36864
	s_add_i32 s49, s48, 1
	s_cmp_lg_u32 s48, 2
	s_cselect_b32 s72, s49, 0
	s_mul_i32 s48, s72, 0xa000
	s_add_i32 s73, s48, 0
	s_add_u32 s48, s74, 0x1c400180
	s_waitcnt lgkmcnt(0)
	v_mfma_f32_32x32x16_bf16 v[2:17], v[62:65], v[54:57], v[2:17]
	ds_read_b128 v[54:57], v68
	s_addc_u32 s49, s75, 0
	s_add_i32 s74, s73, s8
	s_mul_i32 s51, s50, 0xa000
	s_add_i32 s75, s73, s9
	s_add_i32 s76, s73, s45
	s_add_i32 s51, s51, 0
	v_mfma_f32_32x32x16_bf16 v[18:33], v[62:65], v[58:61], v[18:33]
	ds_read_b128 v[58:61], v69 offset:32768
	ds_read_b128 v[62:65], v69 offset:36864
	ds_read_b128 v[66:69], v53
	ds_read_b128 v[70:73], v74 offset:32768
	ds_read_b128 v[74:77], v74 offset:36864
	s_waitcnt vmcnt(5)
	s_waitcnt lgkmcnt(0)
	s_barrier
	s_add_i32 s77, s73, s46
	v_add_u32_e32 v53, s51, v52
	s_add_i32 s73, s47, s73
	v_add_u32_e32 v78, s51, v50
	s_waitcnt lgkmcnt(0)
	v_mfma_f32_32x32x16_bf16 v[2:17], v[54:57], v[58:61], v[2:17]
	v_lshl_add_u64 v[58:59], s[48:49], 0, v[38:39]
	v_lshl_add_u64 v[60:61], s[48:49], 0, v[40:41]
	v_mfma_f32_32x32x16_bf16 v[18:33], v[54:57], v[62:65], v[18:33]
	v_lshl_add_u64 v[54:55], s[48:49], 0, v[34:35]
	v_lshl_add_u64 v[56:57], s[48:49], 0, v[36:37]
	s_mov_b32 s48, m0
	s_mov_b32 m0, s74
	s_nop 0
	global_load_lds_dwordx4 v[54:55], off
	s_mov_b32 m0, s48
	v_add_u32_e32 v54, v53, v51
	s_mov_b32 s48, m0
	s_mov_b32 m0, s75
	s_nop 0
	global_load_lds_dwordx4 v[56:57], off
	s_mov_b32 m0, s48
	v_add_u32_e32 v62, v78, v51
	s_mov_b32 s48, m0
	s_mov_b32 m0, s76
	s_nop 0
	global_load_lds_dwordx4 v[58:59], off
	s_mov_b32 m0, s48
	v_mfma_f32_32x32x16_bf16 v[2:17], v[66:69], v[70:73], v[2:17]
	s_mov_b32 s48, m0
	s_mov_b32 m0, s77
	s_nop 0
	global_load_lds_dwordx4 v[60:61], off
	s_mov_b32 m0, s48
	v_add_u32_e32 v63, v53, v49
	s_mov_b32 s48, m0
	s_mov_b32 m0, s73
	s_nop 0
	global_load_lds_dwordx4 v[42:43], off nt
	s_mov_b32 m0, s48
	ds_read_b128 v[54:57], v54
	ds_read_b128 v[58:61], v62 offset:32768
	s_add_i32 s48, s50, 1
	s_cmp_lg_u32 s50, 2
	s_cselect_b32 s49, s48, 0
	v_mfma_f32_32x32x16_bf16 v[18:33], v[66:69], v[74:77], v[18:33]
	v_add_u32_e32 v66, v78, v48
	s_add_i32 s48, s72, 1
	s_cmp_lg_u32 s72, 2
	s_cselect_b32 s48, s48, 0
	s_add_u32 s6, s6, 0x100
	s_addc_u32 s7, s7, 0
	s_cmpk_eq_i32 s6, 0x1f00
	s_waitcnt lgkmcnt(0)
	v_mfma_f32_32x32x16_bf16 v[2:17], v[54:57], v[58:61], v[2:17]
	ds_read_b128 v[58:61], v62 offset:36864
	ds_read_b128 v[62:65], v63
	v_lshl_add_u64 v[42:43], v[42:43], 0, s[22:23]
	s_waitcnt lgkmcnt(0)
	v_mfma_f32_32x32x16_bf16 v[18:33], v[54:57], v[58:61], v[18:33]
	v_add_u32_e32 v58, v78, v49
	ds_read_b128 v[54:57], v58 offset:32768
	ds_read_b128 v[58:61], v58 offset:36864
	s_waitcnt lgkmcnt(0)
	v_mfma_f32_32x32x16_bf16 v[2:17], v[62:65], v[54:57], v[2:17]
	v_add_u32_e32 v54, v53, v48
	v_add_u32_e32 v53, v53, v47
	v_mfma_f32_32x32x16_bf16 v[18:33], v[62:65], v[58:61], v[18:33]
	ds_read_b128 v[54:57], v54
	ds_read_b128 v[58:61], v66 offset:32768
	s_waitcnt lgkmcnt(0)
	v_mfma_f32_32x32x16_bf16 v[2:17], v[54:57], v[58:61], v[2:17]
	ds_read_b128 v[58:61], v66 offset:36864
	ds_read_b128 v[62:65], v53
	v_add_u32_e32 v53, v78, v47
	s_waitcnt lgkmcnt(0)
	v_mfma_f32_32x32x16_bf16 v[18:33], v[54:57], v[58:61], v[18:33]
	ds_read_b128 v[54:57], v53 offset:32768
	ds_read_b128 v[58:61], v53 offset:36864
	s_waitcnt lgkmcnt(0)
	v_mfma_f32_32x32x16_bf16 v[2:17], v[62:65], v[54:57], v[2:17]
	v_mfma_f32_32x32x16_bf16 v[18:33], v[62:65], v[58:61], v[18:33]
	s_cbranch_scc0 .LBB0_147
	s_mul_i32 s4, s49, 0xa000
	s_add_i32 s4, s4, 0
	s_waitcnt vmcnt(5)
	v_add_u32_e32 v34, s4, v52
	s_waitcnt lgkmcnt(0)
	s_barrier
	v_add_u32_e32 v36, v34, v51
	ds_read_b128 v[36:39], v36
	v_add_u32_e32 v53, s4, v50
	v_add_u32_e32 v54, v53, v51
	ds_read_b128 v[40:43], v54 offset:32768
	s_ashr_i32 s45, s43, 5
	s_cmp_lt_i32 s45, 2
	s_waitcnt lgkmcnt(0)
	v_mfma_f32_32x32x16_bf16 v[2:17], v[36:39], v[40:43], v[2:17]
	ds_read_b128 v[40:43], v54 offset:36864
	v_add_u32_e32 v54, v34, v49
	ds_read_b128 v[54:57], v54
	s_waitcnt lgkmcnt(0)
	v_mfma_f32_32x32x16_bf16 v[18:33], v[36:39], v[40:43], v[18:33]
	v_add_u32_e32 v40, v53, v49
	ds_read_b128 v[36:39], v40 offset:32768
	ds_read_b128 v[40:43], v40 offset:36864
	s_waitcnt lgkmcnt(0)
	v_mfma_f32_32x32x16_bf16 v[2:17], v[54:57], v[36:39], v[2:17]
	v_add_u32_e32 v36, v34, v48
	ds_read_b128 v[36:39], v36
	v_add_u32_e32 v34, v34, v47
	v_mfma_f32_32x32x16_bf16 v[18:33], v[54:57], v[40:43], v[18:33]
	v_add_u32_e32 v54, v53, v48
	ds_read_b128 v[40:43], v54 offset:32768
	s_waitcnt lgkmcnt(0)
	v_mfma_f32_32x32x16_bf16 v[2:17], v[36:39], v[40:43], v[2:17]
	ds_read_b128 v[40:43], v54 offset:36864
	ds_read_b128 v[54:57], v34
	v_add_u32_e32 v34, v53, v47
	s_waitcnt lgkmcnt(0)
	v_mfma_f32_32x32x16_bf16 v[18:33], v[36:39], v[40:43], v[18:33]
	ds_read_b128 v[36:39], v34 offset:32768
	ds_read_b128 v[40:43], v34 offset:36864
	s_waitcnt vmcnt(0)
	v_add_u32_e32 v34, 0, v52
	s_waitcnt lgkmcnt(0)
	s_barrier
	s_waitcnt lgkmcnt(0)
	v_mfma_f32_32x32x16_bf16 v[2:17], v[54:57], v[36:39], v[2:17]
	v_add_u32_e32 v36, v34, v51
	ds_read_b128 v[36:39], v36
	v_mfma_f32_32x32x16_bf16 v[18:33], v[54:57], v[40:43], v[18:33]
	v_add_u32_e32 v54, 0, v50
	v_add_u32_e32 v50, v54, v51
	ds_read_b128 v[40:43], v50 offset:32768
	s_waitcnt lgkmcnt(0)
	v_mfma_f32_32x32x16_bf16 v[2:17], v[36:39], v[40:43], v[2:17]
	ds_read_b128 v[40:43], v50 offset:36864
	v_add_u32_e32 v50, v34, v49
	ds_read_b128 v[50:53], v50
	s_waitcnt lgkmcnt(0)
	v_mfma_f32_32x32x16_bf16 v[18:33], v[36:39], v[40:43], v[18:33]
	v_add_u32_e32 v40, v54, v49
	ds_read_b128 v[36:39], v40 offset:32768
	ds_read_b128 v[40:43], v40 offset:36864
	s_waitcnt lgkmcnt(0)
	v_mfma_f32_32x32x16_bf16 v[2:17], v[50:53], v[36:39], v[2:17]
	v_add_u32_e32 v36, v34, v48
	ds_read_b128 v[36:39], v36
	v_add_u32_e32 v48, v54, v48
	v_add_u32_e32 v34, v34, v47
	v_mfma_f32_32x32x16_bf16 v[18:33], v[50:53], v[40:43], v[18:33]
	ds_read_b128 v[40:43], v48 offset:32768
	s_waitcnt lgkmcnt(0)
	v_mfma_f32_32x32x16_bf16 v[2:17], v[36:39], v[40:43], v[2:17]
	ds_read_b128 v[40:43], v48 offset:36864
	ds_read_b128 v[48:51], v34
	v_add_u32_e32 v34, v54, v47
	s_waitcnt lgkmcnt(0)
	v_mfma_f32_32x32x16_bf16 v[18:33], v[36:39], v[40:43], v[18:33]
	ds_read_b128 v[36:39], v34 offset:32768
	ds_read_b128 v[40:43], v34 offset:36864
	s_waitcnt lgkmcnt(0)
	v_mfma_f32_32x32x16_bf16 v[2:17], v[48:51], v[36:39], v[2:17]
	v_mfma_f32_32x32x16_bf16 v[18:33], v[48:51], v[40:43], v[18:33]
	s_cbranch_scc1 .LBB0_152
	s_cmp_eq_u32 s45, 2
	s_mov_b64 s[4:5], -1
	s_cbranch_scc0 .LBB0_151
	s_mov_b64 s[4:5], 0

.LBB0_553:
	s_mov_b64 s[52:53], s[0:1]
	s_load_dwordx2 s[54:55], s[52:53], 0xa0
	s_mov_b64 s[56:57], s[0:1]
	v_mov_b32_e32 v2, v0
	s_load_dwordx2 s[52:53], s[56:57], 0xa0
	s_and_b32 s46, s44, 3
	v_readfirstlane_b32 s48, v2
	s_ashr_i32 s49, s48, 6
	s_ashr_i32 s45, s44, 2
	s_lshl_b32 s47, s46, 11
	v_bfe_u32 v1, v2, 3, 3
	v_bfe_u32 v45, v2, 5, 1
	v_lshrrev_b32_e32 v6, 1, v2
	s_lshl_b32 s48, s49, 5
	v_bfe_u32 v7, v2, 1, 3
	v_or_b32_e32 v8, 8, v1
	v_or_b32_e32 v9, 24, v1
	v_bitop3_b32 v6, v45, v6, 7 bitop3:0x78
	s_waitcnt lgkmcnt(0)
	s_add_u32 s60, s54, s47
	v_lshlrev_b32_e32 v4, 4, v2
	v_bitop3_b32 v10, v45, v7, 2 bitop3:0x36
	v_bitop3_b32 v11, v45, v7, 4 bitop3:0x36
	v_bitop3_b32 v7, v45, v7, 6 bitop3:0x36
	v_lshrrev_b32_e32 v12, 1, v8
	v_lshrrev_b32_e32 v13, 1, v9
	v_lshl_or_b32 v14, s49, 3, v1
	v_lshlrev_b32_e32 v78, 4, v6
	v_or_b32_e32 v6, s48, v1
	s_addc_u32 s61, s55, 0
	v_and_b32_e32 v5, 48, v2
	v_and_b32_e32 v4, 0x70, v4
	v_lshlrev_b32_e32 v82, 4, v10
	v_lshlrev_b32_e32 v84, 4, v7
	v_or_b32_e32 v7, s48, v8
	v_xor_b32_e32 v8, v12, v2
	v_or_b32_e32 v9, s48, v9
	v_xor_b32_e32 v10, v13, v2
	v_lshrrev_b32_e32 v12, 1, v14
	v_lshlrev_b32_e32 v6, 13, v6
	s_add_u32 s50, s60, 0x34c00000
	v_and_b32_e32 v48, 31, v2
	v_lshlrev_b32_e32 v7, 13, v7
	v_lshlrev_b32_e32 v8, 4, v8
	v_lshlrev_b32_e32 v9, 13, v9
	v_lshlrev_b32_e32 v10, 4, v10
	v_xor_b32_e32 v2, v12, v2
	v_bitop3_b32 v34, v6, v4, v5 bitop3:0xf6
	s_addc_u32 s51, s61, 0
	s_ashr_i32 s54, s44, 4
	v_mov_b32_e32 v39, v35
	v_mov_b32_e32 v41, v35
	v_mov_b32_e32 v37, v35
	v_lshlrev_b32_e32 v83, 4, v11
	v_lshlrev_b32_e32 v11, 7, v14
	v_and_or_b32 v38, v8, s2, v7
	v_and_or_b32 v36, v10, s2, v9
	v_lshlrev_b32_e32 v2, 4, v2
	v_or_b32_e32 v40, 0x20000, v34
	s_ashr_i32 s55, s54, 31
	v_and_or_b32 v2, v2, s2, v11
	s_lshl_b32 s47, s46, 19
	v_lshl_add_u64 v[4:5], s[50:51], 0, v[34:35]
	v_lshl_add_u64 v[6:7], s[50:51], 0, v[38:39]
	v_lshl_add_u64 v[8:9], s[50:51], 0, v[40:41]
	v_lshl_add_u64 v[10:11], s[50:51], 0, v[36:37]
	s_lshl_b64 s[50:51], s[54:55], 21
	s_add_u32 s50, s52, s50
	s_addc_u32 s51, s53, s51
	s_add_u32 s47, s50, s47
	s_addc_u32 s51, s51, 0
	s_lshl_b32 s50, s45, 13
	s_and_b32 s50, s50, 0x6000
	s_add_u32 s50, s47, s50
	s_addc_u32 s51, s51, 0
	s_lshl_b32 s55, s49, 12
	s_lshl_b32 s59, s49, 10
	v_mov_b32_e32 v3, v35
	s_add_i32 s47, s55, 0
	s_or_b32 s58, s55, 0x400
	s_or_b32 s65, s55, 0x800
	s_or_b32 s68, s55, 0xc00
	s_add_i32 s52, s59, 0
	s_mov_b32 s49, m0
	s_mov_b32 m0, s47
	s_nop 0
	global_load_lds_dwordx4 v[4:5], off
	s_mov_b32 m0, s49
	v_lshl_add_u64 v[42:43], s[50:51], 0, v[2:3]
	s_add_i32 s49, s58, 0
	s_add_i32 s50, s65, 0
	s_add_i32 s51, s68, 0
	s_add_i32 s54, s52, 0x8000
	s_mov_b32 s52, m0
	s_mov_b32 m0, s49
	s_nop 0
	global_load_lds_dwordx4 v[6:7], off
	s_mov_b32 m0, s52
	s_add_u32 s56, s60, 0x34c00080
	s_mov_b32 s52, m0
	s_mov_b32 m0, s50
	s_nop 0
	global_load_lds_dwordx4 v[8:9], off
	s_mov_b32 m0, s52
	s_addc_u32 s57, s61, 0
	s_add_i32 s52, s55, s40
	s_add_i32 s53, s58, s40
	s_add_i32 s62, s65, s40
	s_add_i32 s63, s68, s40
	s_add_i32 s64, s59, s41
	s_mov_b32 s66, m0
	s_mov_b32 m0, s51
	s_nop 0
	global_load_lds_dwordx4 v[10:11], off
	s_mov_b32 m0, s66
	v_lshl_add_u64 v[2:3], v[42:43], 0, s[4:5]
	v_lshl_add_u64 v[6:7], s[56:57], 0, v[34:35]
	v_lshl_add_u64 v[8:9], s[56:57], 0, v[38:39]
	v_lshl_add_u64 v[10:11], s[56:57], 0, v[40:41]
	v_lshl_add_u64 v[14:15], s[56:57], 0, v[36:37]
	s_add_u32 s66, s60, 0x34c00100
	s_mov_b32 s56, m0
	s_mov_b32 m0, s54
	s_nop 0
	global_load_lds_dwordx4 v[2:3], off nt
	s_mov_b32 m0, s56
	s_addc_u32 s67, s61, 0
	s_add_i32 s57, s65, s42
	s_mov_b32 s65, m0
	s_mov_b32 m0, s52
	s_nop 0
	global_load_lds_dwordx4 v[6:7], off
	s_mov_b32 m0, s65
	v_lshl_add_u64 v[4:5], v[42:43], 0, s[6:7]
	s_mov_b32 s65, m0
	s_mov_b32 m0, s53
	s_nop 0
	global_load_lds_dwordx4 v[8:9], off
	s_mov_b32 m0, s65
	s_add_i32 s55, s55, s42
	s_mov_b32 s65, m0
	s_mov_b32 m0, s62
	s_nop 0
	global_load_lds_dwordx4 v[10:11], off
	s_mov_b32 m0, s65
	v_lshl_add_u64 v[2:3], s[66:67], 0, v[34:35]
	s_mov_b32 s65, m0
	s_mov_b32 m0, s63
	s_nop 0
	global_load_lds_dwordx4 v[14:15], off
	s_mov_b32 m0, s65
	v_or_b32_e32 v13, s48, v48
	s_mov_b32 s65, m0
	s_mov_b32 m0, s64
	s_nop 0
	global_load_lds_dwordx4 v[4:5], off nt
	s_mov_b32 m0, s65
	s_waitcnt vmcnt(5)
	s_waitcnt lgkmcnt(0)
	s_barrier
	s_add_i32 s56, s58, s42
	s_mov_b32 s65, m0
	s_mov_b32 m0, s55
	s_nop 0
	global_load_lds_dwordx4 v[2:3], off
	s_mov_b32 m0, s65
	v_lshl_add_u64 v[6:7], s[66:67], 0, v[38:39]
	s_mov_b32 s65, m0
	s_mov_b32 m0, s56
	s_nop 0
	global_load_lds_dwordx4 v[6:7], off
	s_mov_b32 m0, s65
	v_lshlrev_b32_e32 v79, 7, v13
	v_lshl_add_u64 v[16:17], s[66:67], 0, v[40:41]
	s_mov_b32 s65, m0
	s_mov_b32 m0, s57
	s_nop 0
	global_load_lds_dwordx4 v[16:17], off
	s_mov_b32 m0, s65
	v_lshlrev_b32_e32 v53, 7, v48
	v_add_u32_e32 v49, 0, v79
	s_add_i32 s58, s68, s42
	v_lshl_add_u64 v[18:19], s[66:67], 0, v[36:37]
	s_mov_b32 s65, m0
	s_mov_b32 m0, s58
	s_nop 0
	global_load_lds_dwordx4 v[18:19], off
	s_mov_b32 m0, s65
	v_add_u32_e32 v46, 0, v53
	v_add_u32_e32 v44, v49, v78
	v_lshl_add_u64 v[12:13], v[42:43], 0, s[8:9]
	s_add_i32 s59, s59, s43
	s_mov_b32 s65, m0
	s_mov_b32 m0, s59
	s_nop 0
	global_load_lds_dwordx4 v[12:13], off nt
	s_mov_b32 m0, s65
	v_add_u32_e32 v1, v46, v78
	ds_read_b128 v[18:21], v44
	ds_read_b128 v[2:5], v1 offset:32768
	v_add_u32_e32 v52, v49, v82
	ds_read_b128 v[22:25], v1 offset:36864
	ds_read_b128 v[58:61], v52
	s_waitcnt lgkmcnt(0)
	v_mfma_f32_32x32x16_bf16 v[2:17], v[18:21], v[2:5], 0
	v_add_u32_e32 v51, v46, v82
	ds_read_b128 v[54:57], v51 offset:32768
	ds_read_b128 v[62:65], v51 offset:36864
	v_add_u32_e32 v50, v49, v83
	v_add_u32_e32 v47, v46, v83
	v_add_u32_e32 v49, v49, v84
	v_add_u32_e32 v46, v46, v84
	s_add_u32 s66, s60, 0x34c00180
	v_mfma_f32_32x32x16_bf16 v[18:33], v[18:21], v[22:25], 0
	s_addc_u32 s67, s61, 0
	v_lshl_add_u64 v[70:71], s[66:67], 0, v[34:35]
	v_lshl_add_u64 v[72:73], s[66:67], 0, v[38:39]
	v_lshl_add_u64 v[74:75], s[66:67], 0, v[40:41]
	v_lshl_add_u64 v[76:77], s[66:67], 0, v[36:37]
	v_add_u32_e32 v80, s41, v53
	s_add_u32 s66, s60, 0x34c00200
	s_waitcnt lgkmcnt(0)
	v_mfma_f32_32x32x16_bf16 v[2:17], v[58:61], v[54:57], v[2:17]
	v_lshl_add_u64 v[54:55], v[42:43], 0, s[10:11]
	v_add_u32_e32 v57, v80, v78
	v_add_u32_e32 v85, s43, v53
	v_add_u32_e32 v86, s42, v79
	s_addc_u32 s67, s61, 0
	v_add_u32_e32 v53, v85, v78
	v_add_u32_e32 v56, v86, v78
	v_mfma_f32_32x32x16_bf16 v[18:33], v[58:61], v[62:65], v[18:33]
	ds_read_b128 v[58:61], v50
	ds_read_b128 v[62:65], v47 offset:32768
	v_lshl_add_u64 v[78:79], s[66:67], 0, v[34:35]
	s_waitcnt lgkmcnt(0)
	v_mfma_f32_32x32x16_bf16 v[2:17], v[58:61], v[62:65], v[2:17]
	ds_read_b128 v[62:65], v47 offset:36864
	ds_read_b128 v[66:69], v49
	s_waitcnt lgkmcnt(0)
	v_mfma_f32_32x32x16_bf16 v[18:33], v[58:61], v[62:65], v[18:33]
	ds_read_b128 v[58:61], v46 offset:32768
	ds_read_b128 v[62:65], v46 offset:36864
	s_waitcnt vmcnt(5)
	s_waitcnt lgkmcnt(0)
	s_barrier
	s_mov_b32 s65, m0
	s_mov_b32 m0, s47
	s_nop 0
	global_load_lds_dwordx4 v[70:71], off
	s_mov_b32 m0, s65
	s_nop 0
	s_mov_b32 s65, m0
	s_mov_b32 m0, s49
	s_nop 0
	global_load_lds_dwordx4 v[72:73], off
	s_mov_b32 m0, s65
	s_waitcnt lgkmcnt(0)
	v_mfma_f32_32x32x16_bf16 v[2:17], v[66:69], v[58:61], v[2:17]
	s_mov_b32 s65, m0
	s_mov_b32 m0, s50
	s_nop 0
	global_load_lds_dwordx4 v[74:75], off
	s_mov_b32 m0, s65
	s_nop 0
	s_mov_b32 s65, m0
	s_mov_b32 m0, s51
	s_nop 0
	global_load_lds_dwordx4 v[76:77], off
	s_mov_b32 m0, s65
	v_lshl_add_u64 v[76:77], v[42:43], 0, s[12:13]
	s_mov_b32 s65, m0
	s_mov_b32 m0, s54
	s_nop 0
	global_load_lds_dwordx4 v[54:55], off nt
	s_mov_b32 m0, s65
	v_add_u32_e32 v54, v80, v82
	v_add_u32_e32 v55, v80, v84
	v_mfma_f32_32x32x16_bf16 v[18:33], v[66:69], v[62:65], v[18:33]
	ds_read_b128 v[58:61], v44 offset:40960
	ds_read_b128 v[62:65], v57
	ds_read_b128 v[66:69], v57 offset:4096
	ds_read_b128 v[70:73], v52 offset:40960
	s_waitcnt lgkmcnt(0)
	v_mfma_f32_32x32x16_bf16 v[2:17], v[58:61], v[62:65], v[2:17]
	v_mfma_f32_32x32x16_bf16 v[18:33], v[58:61], v[66:69], v[18:33]
	ds_read_b128 v[58:61], v54
	ds_read_b128 v[62:65], v54 offset:4096
	s_waitcnt lgkmcnt(0)
	v_mfma_f32_32x32x16_bf16 v[2:17], v[70:73], v[58:61], v[2:17]
	v_add_u32_e32 v58, v80, v83
	v_lshl_add_u64 v[80:81], s[66:67], 0, v[38:39]
	v_add_u32_e32 v59, v85, v82
	v_mfma_f32_32x32x16_bf16 v[18:33], v[70:73], v[62:65], v[18:33]
	ds_read_b128 v[60:63], v50 offset:40960
	ds_read_b128 v[64:67], v58
	ds_read_b128 v[68:71], v58 offset:4096
	ds_read_b128 v[72:75], v49 offset:40960
	s_waitcnt lgkmcnt(0)
	v_mfma_f32_32x32x16_bf16 v[2:17], v[60:63], v[64:67], v[2:17]
	v_mfma_f32_32x32x16_bf16 v[18:33], v[60:63], v[68:71], v[18:33]
	ds_read_b128 v[60:63], v55
	ds_read_b128 v[64:67], v55 offset:4096
	s_waitcnt vmcnt(5)
	s_waitcnt lgkmcnt(0)
	s_barrier
	s_mov_b32 s65, m0
	s_mov_b32 m0, s52
	s_nop 0
	global_load_lds_dwordx4 v[78:79], off
	s_mov_b32 m0, s65
	v_lshl_add_u64 v[68:69], s[66:67], 0, v[40:41]
	s_mov_b32 s65, m0
	s_mov_b32 m0, s53
	s_nop 0
	global_load_lds_dwordx4 v[80:81], off
	s_mov_b32 m0, s65
	v_lshl_add_u64 v[70:71], s[66:67], 0, v[36:37]
	s_waitcnt lgkmcnt(0)
	v_mfma_f32_32x32x16_bf16 v[2:17], v[72:75], v[60:63], v[2:17]
	s_mov_b32 s65, m0
	s_mov_b32 m0, s62
	s_nop 0
	global_load_lds_dwordx4 v[68:69], off
	s_mov_b32 m0, s65
	v_add_u32_e32 v60, v86, v82
	s_mov_b32 s65, m0
	s_mov_b32 m0, s63
	s_nop 0
	global_load_lds_dwordx4 v[70:71], off
	s_mov_b32 m0, s65
	v_add_u32_e32 v61, v85, v83
	s_mov_b32 s65, m0
	s_mov_b32 m0, s64
	s_nop 0
	global_load_lds_dwordx4 v[76:77], off nt
	s_mov_b32 m0, s65
	s_add_u32 s66, s60, 0x34c00280
	s_addc_u32 s67, s61, 0
	v_mfma_f32_32x32x16_bf16 v[18:33], v[72:75], v[64:67], v[18:33]
	ds_read_b128 v[62:65], v56
	ds_read_b128 v[66:69], v53
	v_lshl_add_u64 v[80:81], s[66:67], 0, v[34:35]
	v_lshl_add_u64 v[78:79], v[42:43], 0, s[14:15]
	s_waitcnt lgkmcnt(0)
	v_mfma_f32_32x32x16_bf16 v[2:17], v[62:65], v[66:69], v[2:17]
	ds_read_b128 v[66:69], v53 offset:4096
	ds_read_b128 v[70:73], v60
	s_waitcnt lgkmcnt(0)
	v_mfma_f32_32x32x16_bf16 v[18:33], v[62:65], v[66:69], v[18:33]
	ds_read_b128 v[62:65], v59
	ds_read_b128 v[66:69], v59 offset:4096
	s_waitcnt lgkmcnt(0)
	v_mfma_f32_32x32x16_bf16 v[2:17], v[70:73], v[62:65], v[2:17]
	v_add_u32_e32 v64, v86, v83
	v_add_u32_e32 v63, v86, v84
	v_add_u32_e32 v62, v85, v84
	v_lshl_add_u64 v[82:83], s[66:67], 0, v[38:39]
	v_lshl_add_u64 v[84:85], s[66:67], 0, v[40:41]
	v_lshl_add_u64 v[86:87], s[66:67], 0, v[36:37]
	s_add_u32 s66, s60, 0x34c00300
	v_mfma_f32_32x32x16_bf16 v[18:33], v[70:73], v[66:69], v[18:33]
	ds_read_b128 v[66:69], v64
	ds_read_b128 v[70:73], v61
	s_addc_u32 s67, s61, 0
	s_waitcnt lgkmcnt(0)
	v_mfma_f32_32x32x16_bf16 v[2:17], v[66:69], v[70:73], v[2:17]
	ds_read_b128 v[70:73], v61 offset:4096
	ds_read_b128 v[74:77], v63
	s_waitcnt lgkmcnt(0)
	v_mfma_f32_32x32x16_bf16 v[18:33], v[66:69], v[70:73], v[18:33]
	ds_read_b128 v[66:69], v62
	ds_read_b128 v[70:73], v62 offset:4096
	s_waitcnt vmcnt(5)
	s_waitcnt lgkmcnt(0)
	s_barrier
	s_mov_b32 s65, m0
	s_mov_b32 m0, s55
	s_nop 0
	global_load_lds_dwordx4 v[80:81], off
	s_mov_b32 m0, s65
	v_lshl_add_u64 v[80:81], s[66:67], 0, v[34:35]
	s_mov_b32 s65, m0
	s_mov_b32 m0, s56
	s_nop 0
	global_load_lds_dwordx4 v[82:83], off
	s_mov_b32 m0, s65
	v_lshl_add_u64 v[82:83], s[66:67], 0, v[38:39]
	s_waitcnt lgkmcnt(0)
	v_mfma_f32_32x32x16_bf16 v[2:17], v[74:77], v[66:69], v[2:17]
	s_mov_b32 s65, m0
	s_mov_b32 m0, s57
	s_nop 0
	global_load_lds_dwordx4 v[84:85], off
	s_mov_b32 m0, s65
	v_lshl_add_u64 v[84:85], s[66:67], 0, v[40:41]
	s_mov_b32 s65, m0
	s_mov_b32 m0, s58
	s_nop 0
	global_load_lds_dwordx4 v[86:87], off
	s_mov_b32 m0, s65
	v_lshl_add_u64 v[86:87], s[66:67], 0, v[36:37]
	s_mov_b32 s65, m0
	s_mov_b32 m0, s59
	s_nop 0
	global_load_lds_dwordx4 v[78:79], off nt
	s_mov_b32 m0, s65
	v_lshl_add_u64 v[78:79], v[42:43], 0, s[16:17]
	s_add_u32 s66, s60, 0x34c00380
	v_mfma_f32_32x32x16_bf16 v[18:33], v[74:77], v[70:73], v[18:33]
	ds_read_b128 v[66:69], v44
	ds_read_b128 v[70:73], v1 offset:32768
	s_addc_u32 s67, s61, 0
	s_waitcnt lgkmcnt(0)
	v_mfma_f32_32x32x16_bf16 v[2:17], v[66:69], v[70:73], v[2:17]
	ds_read_b128 v[70:73], v1 offset:36864
	ds_read_b128 v[74:77], v52
	s_waitcnt lgkmcnt(0)
	v_mfma_f32_32x32x16_bf16 v[18:33], v[66:69], v[70:73], v[18:33]
	ds_read_b128 v[66:69], v51 offset:32768
	ds_read_b128 v[70:73], v51 offset:36864
	s_waitcnt lgkmcnt(0)
	v_mfma_f32_32x32x16_bf16 v[2:17], v[74:77], v[66:69], v[2:17]
	v_mfma_f32_32x32x16_bf16 v[18:33], v[74:77], v[70:73], v[18:33]
	ds_read_b128 v[66:69], v50
	ds_read_b128 v[70:73], v47 offset:32768
	s_waitcnt lgkmcnt(0)
	v_mfma_f32_32x32x16_bf16 v[2:17], v[66:69], v[70:73], v[2:17]
	ds_read_b128 v[70:73], v47 offset:36864
	ds_read_b128 v[74:77], v49
	s_waitcnt lgkmcnt(0)
	v_mfma_f32_32x32x16_bf16 v[18:33], v[66:69], v[70:73], v[18:33]
	ds_read_b128 v[66:69], v46 offset:32768
	ds_read_b128 v[70:73], v46 offset:36864
	s_waitcnt vmcnt(5)
	s_waitcnt lgkmcnt(0)
	s_barrier
	s_mov_b32 s65, m0
	s_mov_b32 m0, s47
	s_nop 0
	global_load_lds_dwordx4 v[80:81], off
	s_mov_b32 m0, s65
	s_nop 0
	s_mov_b32 s65, m0
	s_mov_b32 m0, s49
	s_nop 0
	global_load_lds_dwordx4 v[82:83], off
	s_mov_b32 m0, s65
	v_lshl_add_u64 v[82:83], v[42:43], 0, s[18:19]
	s_waitcnt lgkmcnt(0)
	v_mfma_f32_32x32x16_bf16 v[2:17], v[74:77], v[66:69], v[2:17]
	s_mov_b32 s65, m0
	s_mov_b32 m0, s50
	s_nop 0
	global_load_lds_dwordx4 v[84:85], off
	s_mov_b32 m0, s65
	v_lshl_add_u64 v[84:85], s[66:67], 0, v[34:35]
	s_mov_b32 s65, m0
	s_mov_b32 m0, s51
	s_nop 0
	global_load_lds_dwordx4 v[86:87], off
	s_mov_b32 m0, s65
	v_lshl_add_u64 v[86:87], s[66:67], 0, v[38:39]
	s_mov_b32 s65, m0
	s_mov_b32 m0, s54
	s_nop 0
	global_load_lds_dwordx4 v[78:79], off nt
	s_mov_b32 m0, s65
	v_mfma_f32_32x32x16_bf16 v[18:33], v[74:77], v[70:73], v[18:33]
	ds_read_b128 v[66:69], v44 offset:40960
	ds_read_b128 v[70:73], v57
	ds_read_b128 v[74:77], v57 offset:4096
	ds_read_b128 v[78:81], v52 offset:40960
	s_waitcnt lgkmcnt(0)
	v_mfma_f32_32x32x16_bf16 v[2:17], v[66:69], v[70:73], v[2:17]
	v_mfma_f32_32x32x16_bf16 v[18:33], v[66:69], v[74:77], v[18:33]
	ds_read_b128 v[66:69], v54
	ds_read_b128 v[70:73], v54 offset:4096
	s_waitcnt lgkmcnt(0)
	v_mfma_f32_32x32x16_bf16 v[2:17], v[78:81], v[66:69], v[2:17]
	v_mfma_f32_32x32x16_bf16 v[18:33], v[78:81], v[70:73], v[18:33]
	ds_read_b128 v[66:69], v50 offset:40960
	ds_read_b128 v[70:73], v58
	ds_read_b128 v[74:77], v58 offset:4096
	ds_read_b128 v[78:81], v49 offset:40960
	s_waitcnt lgkmcnt(0)
	v_mfma_f32_32x32x16_bf16 v[2:17], v[66:69], v[70:73], v[2:17]
	v_mfma_f32_32x32x16_bf16 v[18:33], v[66:69], v[74:77], v[18:33]
	ds_read_b128 v[66:69], v55
	ds_read_b128 v[70:73], v55 offset:4096
	s_waitcnt vmcnt(5)
	s_waitcnt lgkmcnt(0)
	s_barrier
	s_mov_b32 s65, m0
	s_mov_b32 m0, s52
	s_nop 0
	global_load_lds_dwordx4 v[84:85], off
	s_mov_b32 m0, s65
	v_lshl_add_u64 v[74:75], s[66:67], 0, v[40:41]
	s_mov_b32 s65, m0
	s_mov_b32 m0, s53
	s_nop 0
	global_load_lds_dwordx4 v[86:87], off
	s_mov_b32 m0, s65
	v_lshl_add_u64 v[76:77], s[66:67], 0, v[36:37]
	s_waitcnt lgkmcnt(0)
	v_mfma_f32_32x32x16_bf16 v[2:17], v[78:81], v[66:69], v[2:17]
	s_mov_b32 s65, m0
	s_mov_b32 m0, s62
	s_nop 0
	global_load_lds_dwordx4 v[74:75], off
	s_mov_b32 m0, s65
	s_add_u32 s66, s60, 0x34c00400
	s_mov_b32 s65, m0
	s_mov_b32 m0, s63
	s_nop 0
	global_load_lds_dwordx4 v[76:77], off
	s_mov_b32 m0, s65
	s_addc_u32 s67, s61, 0
	s_mov_b32 s65, m0
	s_mov_b32 m0, s64
	s_nop 0
	global_load_lds_dwordx4 v[82:83], off nt
	s_mov_b32 m0, s65
	v_lshl_add_u64 v[82:83], s[66:67], 0, v[38:39]
	v_lshl_add_u64 v[84:85], s[66:67], 0, v[40:41]
	v_mfma_f32_32x32x16_bf16 v[18:33], v[78:81], v[70:73], v[18:33]
	ds_read_b128 v[66:69], v56
	ds_read_b128 v[70:73], v53
	v_lshl_add_u64 v[80:81], s[66:67], 0, v[34:35]
	v_lshl_add_u64 v[86:87], s[66:67], 0, v[36:37]
	v_lshl_add_u64 v[78:79], v[42:43], 0, s[20:21]
	s_add_u32 s66, s60, 0x34c00480
	s_addc_u32 s67, s61, 0
	s_waitcnt lgkmcnt(0)
	v_mfma_f32_32x32x16_bf16 v[2:17], v[66:69], v[70:73], v[2:17]
	ds_read_b128 v[70:73], v53 offset:4096
	ds_read_b128 v[74:77], v60
	s_waitcnt lgkmcnt(0)
	v_mfma_f32_32x32x16_bf16 v[18:33], v[66:69], v[70:73], v[18:33]
	ds_read_b128 v[66:69], v59
	ds_read_b128 v[70:73], v59 offset:4096
	s_waitcnt lgkmcnt(0)
	v_mfma_f32_32x32x16_bf16 v[2:17], v[74:77], v[66:69], v[2:17]
	v_mfma_f32_32x32x16_bf16 v[18:33], v[74:77], v[70:73], v[18:33]
	ds_read_b128 v[66:69], v64
	ds_read_b128 v[70:73], v61
	s_waitcnt lgkmcnt(0)
	v_mfma_f32_32x32x16_bf16 v[2:17], v[66:69], v[70:73], v[2:17]
	ds_read_b128 v[70:73], v61 offset:4096
	ds_read_b128 v[74:77], v63
	s_waitcnt lgkmcnt(0)
	v_mfma_f32_32x32x16_bf16 v[18:33], v[66:69], v[70:73], v[18:33]
	ds_read_b128 v[66:69], v62
	ds_read_b128 v[70:73], v62 offset:4096
	s_waitcnt vmcnt(5)
	s_waitcnt lgkmcnt(0)
	s_barrier
	s_mov_b32 s65, m0
	s_mov_b32 m0, s55
	s_nop 0
	global_load_lds_dwordx4 v[80:81], off
	s_mov_b32 m0, s65
	v_lshl_add_u64 v[80:81], s[66:67], 0, v[34:35]
	s_mov_b32 s65, m0
	s_mov_b32 m0, s56
	s_nop 0
	global_load_lds_dwordx4 v[82:83], off
	s_mov_b32 m0, s65
	v_lshl_add_u64 v[82:83], s[66:67], 0, v[38:39]
	s_waitcnt lgkmcnt(0)
	v_mfma_f32_32x32x16_bf16 v[2:17], v[74:77], v[66:69], v[2:17]
	s_mov_b32 s65, m0
	s_mov_b32 m0, s57
	s_nop 0
	global_load_lds_dwordx4 v[84:85], off
	s_mov_b32 m0, s65
	v_lshl_add_u64 v[84:85], s[66:67], 0, v[40:41]
	s_mov_b32 s65, m0
	s_mov_b32 m0, s58
	s_nop 0
	global_load_lds_dwordx4 v[86:87], off
	s_mov_b32 m0, s65
	v_lshl_add_u64 v[86:87], s[66:67], 0, v[36:37]
	s_mov_b32 s65, m0
	s_mov_b32 m0, s59
	s_nop 0
	global_load_lds_dwordx4 v[78:79], off nt
	s_mov_b32 m0, s65
	v_lshl_add_u64 v[78:79], v[42:43], 0, s[22:23]
	s_add_u32 s66, s60, 0x34c00500
	v_mfma_f32_32x32x16_bf16 v[18:33], v[74:77], v[70:73], v[18:33]
	ds_read_b128 v[66:69], v44
	ds_read_b128 v[70:73], v1 offset:32768
	s_addc_u32 s67, s61, 0
	s_waitcnt lgkmcnt(0)
	v_mfma_f32_32x32x16_bf16 v[2:17], v[66:69], v[70:73], v[2:17]
	ds_read_b128 v[70:73], v1 offset:36864
	ds_read_b128 v[74:77], v52
	s_waitcnt lgkmcnt(0)
	v_mfma_f32_32x32x16_bf16 v[18:33], v[66:69], v[70:73], v[18:33]
	ds_read_b128 v[66:69], v51 offset:32768
	ds_read_b128 v[70:73], v51 offset:36864
	s_waitcnt lgkmcnt(0)
	v_mfma_f32_32x32x16_bf16 v[2:17], v[74:77], v[66:69], v[2:17]
	v_mfma_f32_32x32x16_bf16 v[18:33], v[74:77], v[70:73], v[18:33]
	ds_read_b128 v[66:69], v50
	ds_read_b128 v[70:73], v47 offset:32768
	s_waitcnt lgkmcnt(0)
	v_mfma_f32_32x32x16_bf16 v[2:17], v[66:69], v[70:73], v[2:17]
	ds_read_b128 v[70:73], v47 offset:36864
	ds_read_b128 v[74:77], v49
	s_waitcnt lgkmcnt(0)
	v_mfma_f32_32x32x16_bf16 v[18:33], v[66:69], v[70:73], v[18:33]
	ds_read_b128 v[66:69], v46 offset:32768
	ds_read_b128 v[70:73], v46 offset:36864
	s_waitcnt vmcnt(5)
	s_waitcnt lgkmcnt(0)
	s_barrier
	s_mov_b32 s65, m0
	s_mov_b32 m0, s47
	s_nop 0
	global_load_lds_dwordx4 v[80:81], off
	s_mov_b32 m0, s65
	s_nop 0
	s_mov_b32 s65, m0
	s_mov_b32 m0, s49
	s_nop 0
	global_load_lds_dwordx4 v[82:83], off
	s_mov_b32 m0, s65
	v_lshl_add_u64 v[82:83], v[42:43], 0, s[24:25]
	s_waitcnt lgkmcnt(0)
	v_mfma_f32_32x32x16_bf16 v[2:17], v[74:77], v[66:69], v[2:17]
	s_mov_b32 s65, m0
	s_mov_b32 m0, s50
	s_nop 0
	global_load_lds_dwordx4 v[84:85], off
	s_mov_b32 m0, s65
	v_lshl_add_u64 v[84:85], s[66:67], 0, v[34:35]
	s_mov_b32 s65, m0
	s_mov_b32 m0, s51
	s_nop 0
	global_load_lds_dwordx4 v[86:87], off
	s_mov_b32 m0, s65
	v_lshl_add_u64 v[86:87], s[66:67], 0, v[38:39]
	s_mov_b32 s65, m0
	s_mov_b32 m0, s54
	s_nop 0
	global_load_lds_dwordx4 v[78:79], off nt
	s_mov_b32 m0, s65
	v_mfma_f32_32x32x16_bf16 v[18:33], v[74:77], v[70:73], v[18:33]
	ds_read_b128 v[66:69], v44 offset:40960
	ds_read_b128 v[70:73], v57
	ds_read_b128 v[74:77], v57 offset:4096
	ds_read_b128 v[78:81], v52 offset:40960
	s_waitcnt lgkmcnt(0)
	v_mfma_f32_32x32x16_bf16 v[2:17], v[66:69], v[70:73], v[2:17]
	v_mfma_f32_32x32x16_bf16 v[18:33], v[66:69], v[74:77], v[18:33]
	ds_read_b128 v[66:69], v54
	ds_read_b128 v[70:73], v54 offset:4096
	s_waitcnt lgkmcnt(0)
	v_mfma_f32_32x32x16_bf16 v[2:17], v[78:81], v[66:69], v[2:17]
	v_mfma_f32_32x32x16_bf16 v[18:33], v[78:81], v[70:73], v[18:33]
	ds_read_b128 v[66:69], v50 offset:40960
	ds_read_b128 v[70:73], v58
	ds_read_b128 v[74:77], v58 offset:4096
	ds_read_b128 v[78:81], v49 offset:40960
	s_waitcnt lgkmcnt(0)
	v_mfma_f32_32x32x16_bf16 v[2:17], v[66:69], v[70:73], v[2:17]
	v_mfma_f32_32x32x16_bf16 v[18:33], v[66:69], v[74:77], v[18:33]
	ds_read_b128 v[66:69], v55
	ds_read_b128 v[70:73], v55 offset:4096
	s_waitcnt vmcnt(5)
	s_waitcnt lgkmcnt(0)
	s_barrier
	s_mov_b32 s65, m0
	s_mov_b32 m0, s52
	s_nop 0
	global_load_lds_dwordx4 v[84:85], off
	s_mov_b32 m0, s65
	v_lshl_add_u64 v[74:75], s[66:67], 0, v[40:41]
	s_mov_b32 s65, m0
	s_mov_b32 m0, s53
	s_nop 0
	global_load_lds_dwordx4 v[86:87], off
	s_mov_b32 m0, s65
	v_lshl_add_u64 v[76:77], s[66:67], 0, v[36:37]
	s_waitcnt lgkmcnt(0)
	v_mfma_f32_32x32x16_bf16 v[2:17], v[78:81], v[66:69], v[2:17]
	s_mov_b32 s65, m0
	s_mov_b32 m0, s62
	s_nop 0
	global_load_lds_dwordx4 v[74:75], off
	s_mov_b32 m0, s65
	s_add_u32 s66, s60, 0x34c00580
	s_mov_b32 s65, m0
	s_mov_b32 m0, s63
	s_nop 0
	global_load_lds_dwordx4 v[76:77], off
	s_mov_b32 m0, s65
	s_addc_u32 s67, s61, 0
	s_mov_b32 s65, m0
	s_mov_b32 m0, s64
	s_nop 0
	global_load_lds_dwordx4 v[82:83], off nt
	s_mov_b32 m0, s65
	v_lshl_add_u64 v[82:83], s[66:67], 0, v[38:39]
	v_lshl_add_u64 v[84:85], s[66:67], 0, v[40:41]
	v_mfma_f32_32x32x16_bf16 v[18:33], v[78:81], v[70:73], v[18:33]
	ds_read_b128 v[66:69], v56
	ds_read_b128 v[70:73], v53
	v_lshl_add_u64 v[80:81], s[66:67], 0, v[34:35]
	v_lshl_add_u64 v[86:87], s[66:67], 0, v[36:37]
	v_lshl_add_u64 v[78:79], v[42:43], 0, s[26:27]
	s_add_u32 s66, s60, 0x34c00600
	s_addc_u32 s67, s61, 0
	s_waitcnt lgkmcnt(0)
	v_mfma_f32_32x32x16_bf16 v[2:17], v[66:69], v[70:73], v[2:17]
	ds_read_b128 v[70:73], v53 offset:4096
	ds_read_b128 v[74:77], v60
	s_waitcnt lgkmcnt(0)
	v_mfma_f32_32x32x16_bf16 v[18:33], v[66:69], v[70:73], v[18:33]
	ds_read_b128 v[66:69], v59
	ds_read_b128 v[70:73], v59 offset:4096
	s_waitcnt lgkmcnt(0)
	v_mfma_f32_32x32x16_bf16 v[2:17], v[74:77], v[66:69], v[2:17]
	v_mfma_f32_32x32x16_bf16 v[18:33], v[74:77], v[70:73], v[18:33]
	ds_read_b128 v[66:69], v64
	ds_read_b128 v[70:73], v61
	s_waitcnt lgkmcnt(0)
	v_mfma_f32_32x32x16_bf16 v[2:17], v[66:69], v[70:73], v[2:17]
	ds_read_b128 v[70:73], v61 offset:4096
	ds_read_b128 v[74:77], v63
	s_waitcnt lgkmcnt(0)
	v_mfma_f32_32x32x16_bf16 v[18:33], v[66:69], v[70:73], v[18:33]
	ds_read_b128 v[66:69], v62
	ds_read_b128 v[70:73], v62 offset:4096
	s_waitcnt vmcnt(5)
	s_waitcnt lgkmcnt(0)
	s_barrier
	s_mov_b32 s65, m0
	s_mov_b32 m0, s55
	s_nop 0
	global_load_lds_dwordx4 v[80:81], off
	s_mov_b32 m0, s65
	v_lshl_add_u64 v[80:81], s[66:67], 0, v[34:35]
	s_mov_b32 s65, m0
	s_mov_b32 m0, s56
	s_nop 0
	global_load_lds_dwordx4 v[82:83], off
	s_mov_b32 m0, s65
	v_lshl_add_u64 v[82:83], s[66:67], 0, v[38:39]
	s_waitcnt lgkmcnt(0)
	v_mfma_f32_32x32x16_bf16 v[2:17], v[74:77], v[66:69], v[2:17]
	s_mov_b32 s65, m0
	s_mov_b32 m0, s57
	s_nop 0
	global_load_lds_dwordx4 v[84:85], off
	s_mov_b32 m0, s65
	v_lshl_add_u64 v[84:85], s[66:67], 0, v[40:41]
	s_mov_b32 s65, m0
	s_mov_b32 m0, s58
	s_nop 0
	global_load_lds_dwordx4 v[86:87], off
	s_mov_b32 m0, s65
	v_lshl_add_u64 v[86:87], s[66:67], 0, v[36:37]
	s_mov_b32 s65, m0
	s_mov_b32 m0, s59
	s_nop 0
	global_load_lds_dwordx4 v[78:79], off nt
	s_mov_b32 m0, s65
	v_lshl_add_u64 v[78:79], v[42:43], 0, s[28:29]
	s_add_u32 s66, s60, 0x34c00680
	v_mfma_f32_32x32x16_bf16 v[18:33], v[74:77], v[70:73], v[18:33]
	ds_read_b128 v[66:69], v44
	ds_read_b128 v[70:73], v1 offset:32768
	s_addc_u32 s67, s61, 0
	s_waitcnt lgkmcnt(0)
	v_mfma_f32_32x32x16_bf16 v[2:17], v[66:69], v[70:73], v[2:17]
	ds_read_b128 v[70:73], v1 offset:36864
	ds_read_b128 v[74:77], v52
	s_waitcnt lgkmcnt(0)
	v_mfma_f32_32x32x16_bf16 v[18:33], v[66:69], v[70:73], v[18:33]
	ds_read_b128 v[66:69], v51 offset:32768
	ds_read_b128 v[70:73], v51 offset:36864
	s_waitcnt lgkmcnt(0)
	v_mfma_f32_32x32x16_bf16 v[2:17], v[74:77], v[66:69], v[2:17]
	v_mfma_f32_32x32x16_bf16 v[18:33], v[74:77], v[70:73], v[18:33]
	ds_read_b128 v[66:69], v50
	ds_read_b128 v[70:73], v47 offset:32768
	s_waitcnt lgkmcnt(0)
	v_mfma_f32_32x32x16_bf16 v[2:17], v[66:69], v[70:73], v[2:17]
	ds_read_b128 v[70:73], v47 offset:36864
	ds_read_b128 v[74:77], v49
	s_waitcnt lgkmcnt(0)
	v_mfma_f32_32x32x16_bf16 v[18:33], v[66:69], v[70:73], v[18:33]
	ds_read_b128 v[66:69], v46 offset:32768
	ds_read_b128 v[70:73], v46 offset:36864
	s_waitcnt vmcnt(5)
	s_waitcnt lgkmcnt(0)
	s_barrier
	s_mov_b32 s65, m0
	s_mov_b32 m0, s47
	s_nop 0
	global_load_lds_dwordx4 v[80:81], off
	s_mov_b32 m0, s65
	s_nop 0
	s_mov_b32 s65, m0
	s_mov_b32 m0, s49
	s_nop 0
	global_load_lds_dwordx4 v[82:83], off
	s_mov_b32 m0, s65
	v_lshl_add_u64 v[82:83], v[42:43], 0, s[30:31]
	s_waitcnt lgkmcnt(0)
	v_mfma_f32_32x32x16_bf16 v[2:17], v[74:77], v[66:69], v[2:17]
	s_mov_b32 s65, m0
	s_mov_b32 m0, s50
	s_nop 0
	global_load_lds_dwordx4 v[84:85], off
	s_mov_b32 m0, s65
	v_lshl_add_u64 v[84:85], s[66:67], 0, v[34:35]
	s_mov_b32 s65, m0
	s_mov_b32 m0, s51
	s_nop 0
	global_load_lds_dwordx4 v[86:87], off
	s_mov_b32 m0, s65
	v_lshl_add_u64 v[86:87], s[66:67], 0, v[38:39]
	s_mov_b32 s65, m0
	s_mov_b32 m0, s54
	s_nop 0
	global_load_lds_dwordx4 v[78:79], off nt
	s_mov_b32 m0, s65
	v_mfma_f32_32x32x16_bf16 v[18:33], v[74:77], v[70:73], v[18:33]
	ds_read_b128 v[66:69], v44 offset:40960
	ds_read_b128 v[70:73], v57
	ds_read_b128 v[74:77], v57 offset:4096
	ds_read_b128 v[78:81], v52 offset:40960
	s_waitcnt lgkmcnt(0)
	v_mfma_f32_32x32x16_bf16 v[2:17], v[66:69], v[70:73], v[2:17]
	v_mfma_f32_32x32x16_bf16 v[18:33], v[66:69], v[74:77], v[18:33]
	ds_read_b128 v[66:69], v54
	ds_read_b128 v[70:73], v54 offset:4096
	s_waitcnt lgkmcnt(0)
	v_mfma_f32_32x32x16_bf16 v[2:17], v[78:81], v[66:69], v[2:17]
	v_mfma_f32_32x32x16_bf16 v[18:33], v[78:81], v[70:73], v[18:33]
	ds_read_b128 v[66:69], v50 offset:40960
	ds_read_b128 v[70:73], v58
	ds_read_b128 v[74:77], v58 offset:4096
	ds_read_b128 v[78:81], v49 offset:40960
	s_waitcnt lgkmcnt(0)
	v_mfma_f32_32x32x16_bf16 v[2:17], v[66:69], v[70:73], v[2:17]
	v_mfma_f32_32x32x16_bf16 v[18:33], v[66:69], v[74:77], v[18:33]
	ds_read_b128 v[66:69], v55
	ds_read_b128 v[70:73], v55 offset:4096
	s_waitcnt vmcnt(5)
	s_waitcnt lgkmcnt(0)
	s_barrier
	s_mov_b32 s65, m0
	s_mov_b32 m0, s52
	s_nop 0
	global_load_lds_dwordx4 v[84:85], off
	s_mov_b32 m0, s65
	s_mov_b32 s52, m0
	s_mov_b32 m0, s53
	s_nop 0
	global_load_lds_dwordx4 v[86:87], off
	s_mov_b32 m0, s52
	v_lshl_add_u64 v[74:75], s[66:67], 0, v[40:41]
	s_mov_b32 s52, m0
	s_mov_b32 m0, s62
	s_nop 0
	global_load_lds_dwordx4 v[74:75], off
	s_mov_b32 m0, s52
	s_waitcnt lgkmcnt(0)
	v_mfma_f32_32x32x16_bf16 v[2:17], v[78:81], v[66:69], v[2:17]
	v_lshl_add_u64 v[76:77], s[66:67], 0, v[36:37]
	s_mov_b32 s52, m0
	s_mov_b32 m0, s63
	s_nop 0
	global_load_lds_dwordx4 v[76:77], off
	s_mov_b32 m0, s52
	s_nop 0
	s_mov_b32 s52, m0
	s_mov_b32 m0, s64
	s_nop 0
	global_load_lds_dwordx4 v[82:83], off nt
	s_mov_b32 m0, s52
	s_add_u32 s52, s60, 0x34c00700
	s_addc_u32 s53, s61, 0
	v_lshl_add_u64 v[82:83], s[52:53], 0, v[38:39]
	v_mfma_f32_32x32x16_bf16 v[18:33], v[78:81], v[70:73], v[18:33]
	ds_read_b128 v[66:69], v56
	ds_read_b128 v[70:73], v53
	v_lshl_add_u64 v[78:79], v[42:43], 0, s[36:37]
	v_lshl_add_u64 v[80:81], v[42:43], 0, s[38:39]
	v_lshl_add_u64 v[42:43], s[52:53], 0, v[34:35]
	v_lshl_add_u64 v[84:85], s[52:53], 0, v[40:41]
	v_lshl_add_u64 v[86:87], s[52:53], 0, v[36:37]
	s_add_u32 s52, s60, 0x34c00780
	s_waitcnt lgkmcnt(0)
	v_mfma_f32_32x32x16_bf16 v[2:17], v[66:69], v[70:73], v[2:17]
	ds_read_b128 v[70:73], v53 offset:4096
	ds_read_b128 v[74:77], v60
	s_addc_u32 s53, s61, 0
	v_lshl_add_u64 v[90:91], s[52:53], 0, v[38:39]
	v_lshl_add_u64 v[92:93], s[52:53], 0, v[40:41]
	s_lshl_b32 s46, s46, 8
	s_ashr_i32 s60, s48, 31
	s_add_u32 s46, s48, s46
	s_waitcnt lgkmcnt(0)
	v_mfma_f32_32x32x16_bf16 v[18:33], v[66:69], v[70:73], v[18:33]
	ds_read_b128 v[66:69], v59
	ds_read_b128 v[70:73], v59 offset:4096
	v_lshl_add_u64 v[88:89], s[52:53], 0, v[34:35]
	s_addc_u32 s48, s60, 0
	v_lshlrev_b32_e32 v34, 2, v48
	v_mov_b32_e32 v95, s48
	v_mov_b32_e32 v97, s48
	v_mov_b32_e32 v99, s48
	s_waitcnt lgkmcnt(0)
	v_mfma_f32_32x32x16_bf16 v[2:17], v[74:77], v[66:69], v[2:17]
	v_mov_b32_e32 v101, s48
	v_mov_b32_e32 v103, s48
	v_mfma_f32_32x32x16_bf16 v[18:33], v[74:77], v[70:73], v[18:33]
	ds_read_b128 v[66:69], v64
	ds_read_b128 v[70:73], v61
	s_waitcnt lgkmcnt(0)
	v_mfma_f32_32x32x16_bf16 v[2:17], v[66:69], v[70:73], v[2:17]
	ds_read_b128 v[70:73], v61 offset:4096
	ds_read_b128 v[74:77], v63
	s_waitcnt lgkmcnt(0)
	v_mfma_f32_32x32x16_bf16 v[18:33], v[66:69], v[70:73], v[18:33]
	ds_read_b128 v[38:41], v62
	ds_read_b128 v[66:69], v62 offset:4096
	s_waitcnt vmcnt(5)
	s_waitcnt lgkmcnt(0)
	s_barrier
	s_mov_b32 s61, m0
	s_mov_b32 m0, s55
	s_nop 0
	global_load_lds_dwordx4 v[42:43], off
	s_mov_b32 m0, s61
	s_mov_b32 s55, m0
	s_mov_b32 m0, s56
	s_nop 0
	global_load_lds_dwordx4 v[82:83], off
	s_mov_b32 m0, s55
	v_mov_b32_e32 v83, s48
	s_mov_b32 s55, m0
	s_mov_b32 m0, s57
	s_nop 0
	global_load_lds_dwordx4 v[84:85], off
	s_mov_b32 m0, s55
	s_waitcnt lgkmcnt(0)
	v_mfma_f32_32x32x16_bf16 v[2:17], v[74:77], v[38:41], v[2:17]
	s_mov_b32 s55, m0
	s_mov_b32 m0, s58
	s_nop 0
	global_load_lds_dwordx4 v[86:87], off
	s_mov_b32 m0, s55
	v_mov_b32_e32 v85, s48
	s_mov_b32 s55, m0
	s_mov_b32 m0, s59
	s_nop 0
	global_load_lds_dwordx4 v[78:79], off nt
	s_mov_b32 m0, s55
	v_mov_b32_e32 v79, s48
	v_mov_b32_e32 v87, s48
	v_mfma_f32_32x32x16_bf16 v[18:33], v[74:77], v[66:69], v[18:33]
	ds_read_b128 v[38:41], v44
	ds_read_b128 v[66:69], v1 offset:32768
	v_lshl_add_u64 v[74:75], s[52:53], 0, v[36:37]
	s_lshl_b32 s52, s45, 6
	s_ashr_i32 s53, s52, 31
	v_lshl_or_b32 v76, v45, 2, s46
	v_mov_b32_e32 v77, s48
	v_or_b32_e32 v78, 1, v76
	s_waitcnt lgkmcnt(0)
	v_mfma_f32_32x32x16_bf16 v[2:17], v[38:41], v[66:69], v[2:17]
	ds_read_b128 v[66:69], v1 offset:36864
	ds_read_b128 v[70:73], v52
	v_or_b32_e32 v82, 2, v76
	v_or_b32_e32 v84, 3, v76
	v_or_b32_e32 v86, 8, v76
	v_or_b32_e32 v94, 9, v76
	v_or_b32_e32 v96, 10, v76
	v_or_b32_e32 v98, 11, v76
	s_waitcnt lgkmcnt(0)
	v_mfma_f32_32x32x16_bf16 v[18:33], v[38:41], v[66:69], v[18:33]
	ds_read_b128 v[36:39], v51 offset:32768
	ds_read_b128 v[40:43], v51 offset:36864
	v_or_b32_e32 v100, 25, v76
	v_or_b32_e32 v102, 26, v76
	v_lshlrev_b64 v[104:105], 14, v[76:77]
	s_waitcnt lgkmcnt(0)
	v_mfma_f32_32x32x16_bf16 v[2:17], v[70:73], v[36:39], v[2:17]
	v_mfma_f32_32x32x16_bf16 v[18:33], v[70:73], v[40:43], v[18:33]
	ds_read_b128 v[36:39], v50
	ds_read_b128 v[40:43], v47 offset:32768
	s_waitcnt lgkmcnt(0)
	v_mfma_f32_32x32x16_bf16 v[2:17], v[36:39], v[40:43], v[2:17]
	ds_read_b128 v[40:43], v47 offset:36864
	ds_read_b128 v[66:69], v49
	s_waitcnt lgkmcnt(0)
	v_mfma_f32_32x32x16_bf16 v[18:33], v[36:39], v[40:43], v[18:33]
	ds_read_b128 v[36:39], v46 offset:32768
	ds_read_b128 v[40:43], v46 offset:36864
	s_waitcnt vmcnt(5)
	s_waitcnt lgkmcnt(0)
	s_barrier
	s_mov_b32 s45, m0
	s_mov_b32 m0, s47
	s_nop 0
	global_load_lds_dwordx4 v[88:89], off
	s_mov_b32 m0, s45
	s_lshl_b64 s[46:47], s[52:53], 2
	s_mov_b32 s45, m0
	s_mov_b32 m0, s49
	s_nop 0
	global_load_lds_dwordx4 v[90:91], off
	s_mov_b32 m0, s45
	s_add_u32 s46, s3, s46
	s_waitcnt lgkmcnt(0)
	v_mfma_f32_32x32x16_bf16 v[2:17], v[66:69], v[36:39], v[2:17]
	s_mov_b32 s45, m0
	s_mov_b32 m0, s50
	s_nop 0
	global_load_lds_dwordx4 v[92:93], off
	s_mov_b32 m0, s45
	v_or_b32_e32 v88, 18, v76
	s_mov_b32 s45, m0
	s_mov_b32 m0, s51
	s_nop 0
	global_load_lds_dwordx4 v[74:75], off
	s_mov_b32 m0, s45
	v_or_b32_e32 v74, 16, v76
	s_mov_b32 s45, m0
	s_mov_b32 m0, s54
	s_nop 0
	global_load_lds_dwordx4 v[80:81], off nt
	s_mov_b32 m0, s45
	v_or_b32_e32 v80, 17, v76
	v_or_b32_e32 v90, 19, v76
	v_mfma_f32_32x32x16_bf16 v[18:33], v[66:69], v[40:43], v[18:33]
	ds_read_b128 v[36:39], v44 offset:40960
	ds_read_b128 v[40:43], v57
	ds_read_b128 v[66:69], v57 offset:4096
	ds_read_b128 v[70:73], v52 offset:40960
	v_or_b32_e32 v92, 24, v76
	v_or_b32_e32 v76, 27, v76
	s_addc_u32 s47, s33, s47
	v_mov_b32_e32 v75, s48
	v_mov_b32_e32 v81, s48
	v_mov_b32_e32 v89, s48
	s_waitcnt lgkmcnt(0)
	v_mfma_f32_32x32x16_bf16 v[2:17], v[36:39], v[40:43], v[2:17]
	v_mov_b32_e32 v91, s48
	v_mov_b32_e32 v93, s48
	s_add_i32 s44, s44, s93
	s_cmpk_lt_i32 s44, 0x100
	v_mfma_f32_32x32x16_bf16 v[18:33], v[36:39], v[66:69], v[18:33]
	ds_read_b128 v[36:39], v54
	ds_read_b128 v[40:43], v54 offset:4096
	s_waitcnt lgkmcnt(0)
	v_mfma_f32_32x32x16_bf16 v[2:17], v[70:73], v[36:39], v[2:17]
	v_mfma_f32_32x32x16_bf16 v[18:33], v[70:73], v[40:43], v[18:33]
	ds_read_b128 v[36:39], v50 offset:40960
	ds_read_b128 v[40:43], v58
	ds_read_b128 v[66:69], v58 offset:4096
	ds_read_b128 v[70:73], v49 offset:40960
	s_waitcnt lgkmcnt(0)
	v_mfma_f32_32x32x16_bf16 v[2:17], v[36:39], v[40:43], v[2:17]
	v_mfma_f32_32x32x16_bf16 v[18:33], v[36:39], v[66:69], v[18:33]
	ds_read_b128 v[36:39], v55
	ds_read_b128 v[40:43], v55 offset:4096
	s_waitcnt vmcnt(5)
	s_waitcnt lgkmcnt(0)
	s_barrier
	v_lshlrev_b64 v[66:67], 14, v[78:79]
	v_lshlrev_b64 v[68:69], 14, v[82:83]
	v_lshlrev_b64 v[78:79], 14, v[84:85]
	v_lshlrev_b64 v[82:83], 14, v[86:87]
	s_waitcnt lgkmcnt(0)
	v_mfma_f32_32x32x16_bf16 v[2:17], v[70:73], v[36:39], v[2:17]
	v_lshlrev_b64 v[84:85], 14, v[94:95]
	v_mfma_f32_32x32x16_bf16 v[18:33], v[70:73], v[40:43], v[18:33]
	ds_read_b128 v[36:39], v56
	ds_read_b128 v[40:43], v53
	v_lshlrev_b64 v[56:57], 14, v[96:97]
	v_lshlrev_b64 v[70:71], 14, v[98:99]
	v_lshlrev_b64 v[72:73], 14, v[74:75]
	v_lshlrev_b64 v[74:75], 14, v[80:81]
	v_lshlrev_b64 v[80:81], 14, v[100:101]
	s_waitcnt lgkmcnt(0)
	v_mfma_f32_32x32x16_bf16 v[2:17], v[36:39], v[40:43], v[2:17]
	ds_read_b128 v[40:43], v53 offset:4096
	s_waitcnt lgkmcnt(0)
	v_mfma_f32_32x32x16_bf16 v[18:33], v[36:39], v[40:43], v[18:33]
	ds_read_b128 v[36:39], v60
	ds_read_b128 v[40:43], v59
	s_waitcnt lgkmcnt(0)
	v_mfma_f32_32x32x16_bf16 v[2:17], v[36:39], v[40:43], v[2:17]
	ds_read_b128 v[40:43], v59 offset:4096
	v_lshlrev_b64 v[58:59], 14, v[88:89]
	s_waitcnt lgkmcnt(0)
	v_mfma_f32_32x32x16_bf16 v[18:33], v[36:39], v[40:43], v[18:33]
	ds_read_b128 v[36:39], v64
	ds_read_b128 v[40:43], v61
	v_lshlrev_b64 v[64:65], 14, v[90:91]
	s_waitcnt lgkmcnt(0)
	v_mfma_f32_32x32x16_bf16 v[2:17], v[36:39], v[40:43], v[2:17]
	ds_read_b128 v[40:43], v61 offset:4096
	v_lshlrev_b64 v[60:61], 14, v[92:93]
	s_waitcnt lgkmcnt(0)
	v_mfma_f32_32x32x16_bf16 v[18:33], v[36:39], v[40:43], v[18:33]
	ds_read_b128 v[36:39], v63
	ds_read_b128 v[40:43], v62
	s_waitcnt lgkmcnt(0)
	v_mfma_f32_32x32x16_bf16 v[2:17], v[36:39], v[40:43], v[2:17]
	ds_read_b128 v[40:43], v62 offset:4096
	s_waitcnt vmcnt(0)
	s_waitcnt lgkmcnt(0)
	s_barrier
	v_lshlrev_b64 v[62:63], 14, v[76:77]
	v_lshl_add_u64 v[76:77], s[46:47], 0, v[34:35]
	v_lshl_add_u64 v[86:87], v[76:77], 0, v[104:105]
	v_lshl_add_u64 v[66:67], v[76:77], 0, v[66:67]
	s_waitcnt lgkmcnt(0)
	v_mfma_f32_32x32x16_bf16 v[18:33], v[36:39], v[40:43], v[18:33]
	ds_read_b128 v[36:39], v44
	ds_read_b128 v[40:43], v1 offset:32768
	v_lshlrev_b64 v[44:45], 14, v[102:103]
	v_lshl_add_u64 v[68:69], v[76:77], 0, v[68:69]
	v_lshl_add_u64 v[78:79], v[76:77], 0, v[78:79]
	v_lshl_add_u64 v[82:83], v[76:77], 0, v[82:83]
	v_lshl_add_u64 v[44:45], v[76:77], 0, v[44:45]
	v_lshl_add_u64 v[62:63], v[76:77], 0, v[62:63]
	s_waitcnt lgkmcnt(0)
	v_mfma_f32_32x32x16_bf16 v[2:17], v[36:39], v[40:43], v[2:17]
	ds_read_b128 v[40:43], v1 offset:36864
	ds_read_b128 v[52:55], v52
	s_waitcnt lgkmcnt(0)
	v_mfma_f32_32x32x16_bf16 v[18:33], v[36:39], v[40:43], v[18:33]
	ds_read_b128 v[36:39], v51 offset:32768
	ds_read_b128 v[40:43], v51 offset:36864
	s_waitcnt lgkmcnt(0)
	v_mfma_f32_32x32x16_bf16 v[2:17], v[52:55], v[36:39], v[2:17]
	v_mfma_f32_32x32x16_bf16 v[18:33], v[52:55], v[40:43], v[18:33]
	ds_read_b128 v[36:39], v50
	ds_read_b128 v[40:43], v47 offset:32768
	v_lshl_add_u64 v[52:53], v[76:77], 0, v[84:85]
	v_lshl_add_u64 v[54:55], v[76:77], 0, v[56:57]
	v_lshl_add_u64 v[56:57], v[76:77], 0, v[70:71]
	v_lshl_add_u64 v[70:71], v[76:77], 0, v[72:73]
	s_waitcnt lgkmcnt(0)
	v_mfma_f32_32x32x16_bf16 v[2:17], v[36:39], v[40:43], v[2:17]
	ds_read_b128 v[40:43], v47 offset:36864
	ds_read_b128 v[48:51], v49
	s_waitcnt lgkmcnt(0)
	v_mfma_f32_32x32x16_bf16 v[18:33], v[36:39], v[40:43], v[18:33]
	ds_read_b128 v[36:39], v46 offset:32768
	ds_read_b128 v[40:43], v46 offset:36864
	v_lshl_add_u64 v[46:47], v[76:77], 0, v[64:65]
	s_waitcnt lgkmcnt(0)
	v_mfma_f32_32x32x16_bf16 v[2:17], v[48:51], v[36:39], v[2:17]
	v_lshl_add_u64 v[36:37], v[76:77], 0, v[74:75]
	v_lshl_add_u64 v[38:39], v[76:77], 0, v[58:59]
	v_lshl_add_u64 v[58:59], v[76:77], 0, v[60:61]
	v_lshl_add_u64 v[60:61], v[76:77], 0, v[80:81]
	v_mfma_f32_32x32x16_bf16 v[18:33], v[48:51], v[40:43], v[18:33]
	s_nop 6
	global_store_dword v[86:87], v2, off
	s_nop 3
	global_store_dword v[86:87], v18, off offset:128
	global_store_dword v[66:67], v3, off
	global_store_dword v[66:67], v19, off offset:128
	global_store_dword v[68:69], v4, off
	global_store_dword v[68:69], v20, off offset:128
	global_store_dword v[78:79], v5, off
	global_store_dword v[78:79], v21, off offset:128
	global_store_dword v[82:83], v6, off
	global_store_dword v[82:83], v22, off offset:128
	global_store_dword v[52:53], v7, off
	global_store_dword v[52:53], v23, off offset:128
	global_store_dword v[54:55], v8, off
	global_store_dword v[54:55], v24, off offset:128
	global_store_dword v[56:57], v9, off
	global_store_dword v[56:57], v25, off offset:128
	global_store_dword v[70:71], v10, off
	global_store_dword v[70:71], v26, off offset:128
	global_store_dword v[36:37], v11, off
	global_store_dword v[36:37], v27, off offset:128
	global_store_dword v[38:39], v12, off
	global_store_dword v[38:39], v28, off offset:128
	global_store_dword v[46:47], v13, off
	global_store_dword v[46:47], v29, off offset:128
	global_store_dword v[58:59], v14, off
	global_store_dword v[58:59], v30, off offset:128
	global_store_dword v[60:61], v15, off
	global_store_dword v[60:61], v31, off offset:128
	global_store_dword v[44:45], v16, off
	global_store_dword v[44:45], v32, off offset:128
	global_store_dword v[62:63], v17, off
	global_store_dword v[62:63], v33, off offset:128
	s_waitcnt lgkmcnt(0)
	s_waitcnt vmcnt(0)
	s_barrier
	s_cbranch_scc1 .LBB0_553

.LBB0_700:
	s_mov_b64 s[4:5], s[0:1]
	s_load_dwordx2 s[4:5], s[4:5], 0xa0
	s_mov_b64 s[20:21], s[0:1]
	v_mov_b32_e32 v3, v0
	s_load_dwordx2 s[20:21], s[20:21], 0xa0
	s_waitcnt lgkmcnt(0)
	s_add_u32 s30, s4, 0x41200000
	s_addc_u32 s31, s5, 0
	v_readfirstlane_b32 s26, v3
	s_ashr_i32 s33, s26, 6
	s_lshl_b32 s26, s33, 5
	v_bfe_u32 v2, v3, 3, 3
	v_or_b32_e32 v4, s26, v2
	v_lshlrev_b32_e32 v5, 4, v3
	v_lshlrev_b32_e32 v4, 7, v4
	v_and_b32_e32 v6, 48, v3
	v_and_b32_e32 v5, 0x70, v5
	v_bitop3_b32 v42, v4, v5, v6 bitop3:0xf6
	v_or_b32_e32 v4, 8, v2
	v_or_b32_e32 v5, s26, v4
	v_lshrrev_b32_e32 v4, 1, v4
	v_xor_b32_e32 v4, v4, v3
	s_ashr_i32 s28, s25, 2
	v_lshlrev_b32_e32 v5, 7, v5
	v_lshlrev_b32_e32 v4, 4, v4
	s_ashr_i32 s29, s28, 31
	v_and_or_b32 v34, v4, s2, v5
	v_or_b32_e32 v4, 24, v2
	s_lshl_b64 s[28:29], s[28:29], 21
	v_or_b32_e32 v5, s26, v4
	v_lshrrev_b32_e32 v4, 1, v4
	s_add_u32 s20, s20, s28
	v_xor_b32_e32 v4, v4, v3
	s_addc_u32 s21, s21, s29
	s_lshl_b32 s27, s25, 13
	v_lshlrev_b32_e32 v5, 7, v5
	v_lshlrev_b32_e32 v4, 4, v4
	v_lshl_or_b32 v2, s33, 3, v2
	s_and_b32 s27, s27, 0x6000
	v_and_or_b32 v36, v4, s2, v5
	v_lshlrev_b32_e32 v4, 7, v2
	v_lshrrev_b32_e32 v2, 1, v2
	s_add_u32 s20, s20, s27
	v_xor_b32_e32 v2, v2, v3
	s_addc_u32 s21, s21, 0
	s_lshl_b32 s27, s33, 12
	v_lshlrev_b32_e32 v2, 4, v2
	s_add_i32 s28, s27, 0
	v_and_or_b32 v2, v2, s2, v4
	v_lshl_add_u64 v[4:5], s[30:31], 0, v[42:43]
	s_mov_b32 s29, m0
	s_mov_b32 m0, s28
	s_nop 0
	global_load_lds_dwordx4 v[4:5], off
	s_mov_b32 m0, s29
	s_or_b32 s28, s27, 0x400
	v_mov_b32_e32 v35, v43
	s_add_i32 s29, s28, 0
	v_and_b32_e32 v48, 31, v3
	v_bfe_u32 v40, v3, 5, 1
	v_lshrrev_b32_e32 v9, 1, v3
	v_bfe_u32 v10, v3, 1, 3
	v_lshl_add_u64 v[6:7], s[30:31], 0, v[34:35]
	s_mov_b32 s36, m0
	s_mov_b32 m0, s29
	s_nop 0
	global_load_lds_dwordx4 v[6:7], off
	s_mov_b32 m0, s36
	v_lshl_add_u64 v[4:5], v[4:5], 0, s[12:13]
	s_or_b32 s29, s27, 0x800
	v_mov_b32_e32 v37, v43
	v_mov_b32_e32 v3, v43
	s_add_i32 s36, s29, 0
	s_mov_b32 s37, m0
	s_mov_b32 m0, s36
	s_nop 0
	global_load_lds_dwordx4 v[4:5], off
	s_mov_b32 m0, s37
	v_lshl_add_u64 v[4:5], s[30:31], 0, v[36:37]
	s_or_b32 s30, s27, 0xc00
	v_lshl_add_u64 v[2:3], s[20:21], 0, v[2:3]
	s_lshl_b32 s20, s33, 10
	s_add_i32 s31, s30, 0
	s_add_i32 s33, s20, 0
	s_mov_b32 s36, m0
	s_mov_b32 m0, s31
	s_nop 0
	global_load_lds_dwordx4 v[4:5], off
	s_mov_b32 m0, s36
	s_add_i32 s31, s20, 0x8000
	s_add_i32 s20, s33, 0x8000
	v_lshl_add_u64 v[38:39], v[2:3], 0, s[14:15]
	s_mov_b32 s21, m0
	s_mov_b32 m0, s20
	s_nop 0
	global_load_lds_dwordx4 v[38:39], off nt
	s_mov_b32 m0, s21
	s_add_u32 s20, s4, 0x41208000
	s_addc_u32 s21, s5, 0
	v_lshl_add_u64 v[4:5], s[20:21], 0, v[42:43]
	s_add_i32 s36, s27, s3
	s_mov_b32 s37, m0
	s_mov_b32 m0, s36
	s_nop 0
	global_load_lds_dwordx4 v[4:5], off
	s_mov_b32 m0, s37
	v_lshl_add_u64 v[6:7], s[20:21], 0, v[34:35]
	s_add_i32 s36, s28, s3
	s_mov_b32 s37, m0
	s_mov_b32 m0, s36
	s_nop 0
	global_load_lds_dwordx4 v[6:7], off
	s_mov_b32 m0, s37
	v_lshl_add_u64 v[4:5], v[4:5], 0, s[12:13]
	s_add_i32 s36, s29, s3
	s_mov_b32 s37, m0
	s_mov_b32 m0, s36
	s_nop 0
	global_load_lds_dwordx4 v[4:5], off
	s_mov_b32 m0, s37
	v_lshl_add_u64 v[4:5], s[20:21], 0, v[36:37]
	s_add_i32 s20, s30, s3
	s_mov_b32 s21, m0
	s_mov_b32 m0, s20
	s_nop 0
	global_load_lds_dwordx4 v[4:5], off
	s_mov_b32 m0, s21
	v_lshl_add_u64 v[2:3], v[2:3], 0, s[16:17]
	s_add_i32 s33, s33, 0x12000
	s_mov_b32 s20, m0
	s_mov_b32 m0, s33
	s_nop 0
	global_load_lds_dwordx4 v[2:3], off nt
	s_mov_b32 m0, s20
	v_bitop3_b32 v2, v40, v9, 7 bitop3:0x78
	v_lshlrev_b32_e32 v53, 4, v2
	v_bitop3_b32 v2, v40, v10, 2 bitop3:0x36
	v_lshlrev_b32_e32 v51, 4, v2
	v_bitop3_b32 v2, v40, v10, 4 bitop3:0x36
	v_or_b32_e32 v8, s26, v48
	v_lshlrev_b32_e32 v49, 4, v2
	v_bitop3_b32 v2, v40, v10, 6 bitop3:0x36
	v_lshlrev_b32_e32 v54, 7, v8
	v_lshlrev_b32_e32 v52, 7, v48
	v_lshlrev_b32_e32 v50, 4, v2
	s_mov_b64 s[20:21], 0
	s_mov_b32 s36, 0
	s_mov_b32 s33, 2
	v_mov_b32_e32 v2, v43
	v_mov_b32_e32 v3, v43
	v_mov_b32_e32 v4, v43
	v_mov_b32_e32 v5, v43
	v_mov_b32_e32 v6, v43
	v_mov_b32_e32 v7, v43
	v_mov_b32_e32 v8, v43
	v_mov_b32_e32 v9, v43
	v_mov_b32_e32 v10, v43
	v_mov_b32_e32 v11, v43
	v_mov_b32_e32 v12, v43
	v_mov_b32_e32 v13, v43
	v_mov_b32_e32 v14, v43
	v_mov_b32_e32 v15, v43
	v_mov_b32_e32 v16, v43
	v_mov_b32_e32 v17, v43
	v_mov_b32_e32 v18, v43
	v_mov_b32_e32 v19, v43
	v_mov_b32_e32 v20, v43
	v_mov_b32_e32 v21, v43
	v_mov_b32_e32 v22, v43
	v_mov_b32_e32 v23, v43
	v_mov_b32_e32 v24, v43
	v_mov_b32_e32 v25, v43
	v_mov_b32_e32 v26, v43
	v_mov_b32_e32 v27, v43
	v_mov_b32_e32 v28, v43
	v_mov_b32_e32 v29, v43
	v_mov_b32_e32 v30, v43
	v_mov_b32_e32 v31, v43
	v_mov_b32_e32 v32, v43
	v_mov_b32_e32 v33, v43
.LBB0_701:
	s_mul_i32 s37, s33, 0xa000
	s_add_i32 s37, s37, 0
	s_add_u32 s41, s4, s20
	s_addc_u32 s42, s5, s21
	s_waitcnt vmcnt(5)
	s_mul_i32 s40, s36, 0xa000
	s_add_u32 s38, s41, 0x41210000
	s_waitcnt lgkmcnt(0)
	s_barrier
	s_addc_u32 s39, s42, 0
	s_add_i32 s43, s37, s27
	s_add_i32 s44, s37, s28
	s_add_i32 s45, s37, s29
	s_add_i32 s46, s37, s30
	s_add_i32 s37, s31, s37
	s_add_i32 s40, s40, 0
	s_add_i32 s47, s36, 1
	v_lshl_add_u64 v[58:59], s[38:39], 0, v[42:43]
	s_cmp_lg_u32 s36, 2
	s_mov_b32 s36, m0
	s_mov_b32 m0, s43
	s_nop 0
	global_load_lds_dwordx4 v[58:59], off
	s_mov_b32 m0, s36
	v_lshl_add_u64 v[60:61], s[38:39], 0, v[34:35]
	s_mov_b32 s36, m0
	s_mov_b32 m0, s44
	s_nop 0
	global_load_lds_dwordx4 v[60:61], off
	s_mov_b32 m0, s36
	v_lshl_add_u64 v[58:59], v[58:59], 0, s[12:13]
	s_mov_b32 s36, m0
	s_mov_b32 m0, s45
	s_nop 0
	global_load_lds_dwordx4 v[58:59], off
	s_mov_b32 m0, s36
	v_lshl_add_u64 v[44:45], v[38:39], 0, s[20:21]
	v_lshl_add_u64 v[62:63], s[38:39], 0, v[36:37]
	v_add_u32_e32 v41, s40, v54
	s_mov_b32 s36, m0
	s_mov_b32 m0, s46
	s_nop 0
	global_load_lds_dwordx4 v[62:63], off
	s_mov_b32 m0, s36
	v_lshl_add_u64 v[56:57], v[44:45], 0, s[6:7]
	v_add_u32_e32 v47, s40, v52
	v_add_u32_e32 v55, v41, v53
	s_mov_b32 s36, m0
	s_mov_b32 m0, s37
	s_nop 0
	global_load_lds_dwordx4 v[56:57], off nt
	s_mov_b32 m0, s36
	v_add_u32_e32 v64, v47, v53
	ds_read_b128 v[56:59], v55
	ds_read_b128 v[60:63], v64 offset:32768
	v_add_u32_e32 v65, v41, v51
	s_waitcnt lgkmcnt(0)
	v_mfma_f32_32x32x16_bf16 v[2:17], v[56:59], v[60:63], v[2:17]
	ds_read_b128 v[60:63], v64 offset:36864
	ds_read_b128 v[64:67], v65
	v_add_u32_e32 v68, v47, v51
	v_add_u32_e32 v69, v41, v49
	v_add_u32_e32 v55, v47, v49
	v_add_u32_e32 v41, v41, v50
	v_add_u32_e32 v47, v47, v50
	s_cselect_b32 s38, s47, 0
	s_waitcnt lgkmcnt(0)
	v_mfma_f32_32x32x16_bf16 v[18:33], v[56:59], v[60:63], v[18:33]
	ds_read_b128 v[56:59], v68 offset:32768
	ds_read_b128 v[60:63], v68 offset:36864
	s_add_i32 s36, s33, 1
	s_cmp_lg_u32 s33, 2
	s_cselect_b32 s39, s36, 0
	s_mul_i32 s36, s39, 0xa000
	s_add_i32 s40, s36, 0
	s_mul_i32 s33, s38, 0xa000
	s_waitcnt lgkmcnt(0)
	v_mfma_f32_32x32x16_bf16 v[2:17], v[64:67], v[56:59], v[2:17]
	ds_read_b128 v[56:59], v69
	s_add_u32 s36, s41, 0x41218000
	s_addc_u32 s37, s42, 0
	s_add_i32 s33, s33, 0
	s_add_i32 s41, s40, s27
	s_add_i32 s42, s40, s28
	s_add_i32 s43, s40, s29
	v_mfma_f32_32x32x16_bf16 v[18:33], v[64:67], v[60:63], v[18:33]
	ds_read_b128 v[60:63], v55 offset:32768
	ds_read_b128 v[64:67], v55 offset:36864
	ds_read_b128 v[68:71], v41
	ds_read_b128 v[72:75], v47 offset:32768
	ds_read_b128 v[76:79], v47 offset:36864
	s_waitcnt vmcnt(5)
	s_waitcnt lgkmcnt(0)
	s_barrier
	v_add_u32_e32 v41, s33, v54
	v_add_u32_e32 v47, s33, v52
	s_add_i32 s44, s40, s30
	v_lshl_add_u64 v[44:45], v[44:45], 0, s[18:19]
	s_waitcnt lgkmcnt(0)
	v_mfma_f32_32x32x16_bf16 v[2:17], v[56:59], v[60:63], v[2:17]
	v_lshl_add_u64 v[60:61], s[36:37], 0, v[36:37]
	s_add_i32 s40, s31, s40
	v_add_u32_e32 v55, v41, v53
	v_mfma_f32_32x32x16_bf16 v[18:33], v[56:59], v[64:67], v[18:33]
	v_lshl_add_u64 v[56:57], s[36:37], 0, v[42:43]
	s_mov_b32 s33, m0
	s_mov_b32 m0, s41
	s_nop 0
	global_load_lds_dwordx4 v[56:57], off
	s_mov_b32 m0, s33
	v_lshl_add_u64 v[58:59], s[36:37], 0, v[34:35]
	s_mov_b32 s33, m0
	s_mov_b32 m0, s42
	s_nop 0
	global_load_lds_dwordx4 v[58:59], off
	s_mov_b32 m0, s33
	v_lshl_add_u64 v[56:57], v[56:57], 0, s[12:13]
	s_mov_b32 s33, m0
	s_mov_b32 m0, s43
	s_nop 0
	global_load_lds_dwordx4 v[56:57], off
	s_mov_b32 m0, s33
	v_add_u32_e32 v64, v47, v53
	v_mfma_f32_32x32x16_bf16 v[2:17], v[68:71], v[72:75], v[2:17]
	s_mov_b32 s33, m0
	s_mov_b32 m0, s44
	s_nop 0
	global_load_lds_dwordx4 v[60:61], off
	s_mov_b32 m0, s33
	s_nop 0
	s_mov_b32 s33, m0
	s_mov_b32 m0, s40
	s_nop 0
	global_load_lds_dwordx4 v[44:45], off nt
	s_mov_b32 m0, s33
	ds_read_b128 v[56:59], v55
	ds_read_b128 v[60:63], v64 offset:32768
	v_add_u32_e32 v44, v41, v51
	v_add_u32_e32 v45, v47, v49
	s_add_i32 s33, s38, 1
	v_mfma_f32_32x32x16_bf16 v[18:33], v[68:71], v[76:79], v[18:33]
	s_cmp_lg_u32 s38, 2
	s_cselect_b32 s36, s33, 0
	s_add_i32 s33, s39, 1
	s_cmp_lg_u32 s39, 2
	s_cselect_b32 s33, s33, 0
	s_add_u32 s20, s20, 0x10000
	s_addc_u32 s21, s21, 0
	s_waitcnt lgkmcnt(0)
	v_mfma_f32_32x32x16_bf16 v[2:17], v[56:59], v[60:63], v[2:17]
	ds_read_b128 v[60:63], v64 offset:36864
	ds_read_b128 v[64:67], v44
	v_add_u32_e32 v44, v47, v51
	s_cmp_lg_u32 s20, 0x1f0000
	s_waitcnt lgkmcnt(0)
	v_mfma_f32_32x32x16_bf16 v[18:33], v[56:59], v[60:63], v[18:33]
	ds_read_b128 v[56:59], v44 offset:32768
	ds_read_b128 v[60:63], v44 offset:36864
	v_add_u32_e32 v44, v41, v49
	v_add_u32_e32 v41, v41, v50
	s_waitcnt lgkmcnt(0)
	v_mfma_f32_32x32x16_bf16 v[2:17], v[64:67], v[56:59], v[2:17]
	v_mfma_f32_32x32x16_bf16 v[18:33], v[64:67], v[60:63], v[18:33]
	ds_read_b128 v[56:59], v44
	ds_read_b128 v[60:63], v45 offset:32768
	s_waitcnt lgkmcnt(0)
	v_mfma_f32_32x32x16_bf16 v[2:17], v[56:59], v[60:63], v[2:17]
	ds_read_b128 v[60:63], v45 offset:36864
	ds_read_b128 v[64:67], v41
	v_add_u32_e32 v41, v47, v50
	s_waitcnt lgkmcnt(0)
	v_mfma_f32_32x32x16_bf16 v[18:33], v[56:59], v[60:63], v[18:33]
	ds_read_b128 v[56:59], v41 offset:32768
	ds_read_b128 v[60:63], v41 offset:36864
	s_waitcnt lgkmcnt(0)
	v_mfma_f32_32x32x16_bf16 v[2:17], v[64:67], v[56:59], v[2:17]
	v_mfma_f32_32x32x16_bf16 v[18:33], v[64:67], v[60:63], v[18:33]
	s_cbranch_scc1 .LBB0_701
	s_mul_i32 s4, s36, 0xa000
	s_add_i32 s4, s4, 0
	s_waitcnt vmcnt(5)
	v_add_u32_e32 v38, s4, v54
	s_waitcnt lgkmcnt(0)
	s_barrier
	v_add_u32_e32 v34, v38, v53
	ds_read_b128 v[34:37], v34
	v_add_u32_e32 v39, s4, v52
	v_add_u32_e32 v41, v39, v53
	ds_read_b128 v[56:59], v41 offset:32768
	v_lshl_or_b32 v47, v40, 2, s26
	v_add_u32_e32 v44, 0x2000, v47
	v_ashrrev_i32_e32 v45, 31, v44
	s_waitcnt lgkmcnt(0)
	v_mfma_f32_32x32x16_bf16 v[2:17], v[34:37], v[56:59], v[2:17]
	ds_read_b128 v[56:59], v41 offset:36864
	v_add_u32_e32 v41, v38, v51
	ds_read_b128 v[60:63], v41
	v_add_u32_e32 v41, v39, v51
	v_add_u32_e32 v42, 0, v54
	v_add_u32_e32 v64, v42, v49
	v_add_u32_e32 v76, 0x2008, v47
	s_waitcnt lgkmcnt(0)
	v_mfma_f32_32x32x16_bf16 v[18:33], v[34:37], v[56:59], v[18:33]
	ds_read_b128 v[34:37], v41 offset:32768
	ds_read_b128 v[56:59], v41 offset:36864
	v_add_u32_e32 v41, v39, v49
	v_ashrrev_i32_e32 v77, 31, v76
	s_waitcnt lgkmcnt(0)
	v_mfma_f32_32x32x16_bf16 v[2:17], v[60:63], v[34:37], v[2:17]
	v_add_u32_e32 v34, v38, v49
	ds_read_b128 v[34:37], v34
	v_add_u32_e32 v38, v38, v50
	v_mfma_f32_32x32x16_bf16 v[18:33], v[60:63], v[56:59], v[18:33]
	ds_read_b128 v[56:59], v41 offset:32768
	ds_read_b128 v[60:63], v38
	v_add_u32_e32 v38, v39, v50
	s_waitcnt lgkmcnt(0)
	v_mfma_f32_32x32x16_bf16 v[2:17], v[34:37], v[56:59], v[2:17]
	ds_read_b128 v[56:59], v41 offset:36864
	s_waitcnt lgkmcnt(0)
	v_mfma_f32_32x32x16_bf16 v[18:33], v[34:37], v[56:59], v[18:33]
	ds_read_b128 v[34:37], v38 offset:32768
	ds_read_b128 v[56:59], v38 offset:36864
	s_waitcnt vmcnt(0)
	s_waitcnt lgkmcnt(0)
	s_barrier
	v_lshl_add_u64 v[38:39], v[44:45], 2, s[8:9]
	global_load_dwordx4 v[38:41], v[38:39], off
	v_add_u32_e32 v45, 0, v52
	v_add_u32_e32 v49, v45, v49
	s_waitcnt lgkmcnt(0)
	v_mfma_f32_32x32x16_bf16 v[2:17], v[60:63], v[34:37], v[2:17]
	v_add_u32_e32 v34, v42, v53
	ds_read_b128 v[34:37], v34
	v_mfma_f32_32x32x16_bf16 v[18:33], v[60:63], v[56:59], v[18:33]
	v_add_u32_e32 v56, v45, v53
	ds_read_b128 v[52:55], v56 offset:32768
	v_add_u32_e32 v57, v42, v51
	v_add_u32_e32 v60, v45, v51
	v_add_u32_e32 v42, v42, v50
	v_add_u32_e32 v45, v45, v50
	s_waitcnt lgkmcnt(0)
	v_mfma_f32_32x32x16_bf16 v[2:17], v[34:37], v[52:55], v[2:17]
	ds_read_b128 v[52:55], v56 offset:36864
	ds_read_b128 v[56:59], v57
	s_waitcnt lgkmcnt(0)
	v_mfma_f32_32x32x16_bf16 v[18:33], v[34:37], v[52:55], v[18:33]
	ds_read_b128 v[50:53], v60 offset:32768
	v_lshl_add_u64 v[34:35], v[76:77], 2, s[8:9]
	ds_read_b128 v[60:63], v60 offset:36864
	global_load_dwordx4 v[34:37], v[34:35], off
	s_waitcnt vmcnt(0)
	v_fmamk_f32 v38, v38, 0x39800000, v1
	s_waitcnt lgkmcnt(1)
	v_mfma_f32_32x32x16_bf16 v[2:17], v[56:59], v[50:53], v[2:17]
	v_mul_f32_e32 v50, 0x4f800000, v38
	v_cmp_gt_f32_e32 vcc, s22, v38
	s_nop 1
	v_cndmask_b32_e32 v38, v38, v50, vcc
	v_sqrt_f32_e32 v54, v38
	ds_read_b128 v[50:53], v64
	ds_read_b128 v[64:67], v49 offset:32768
	ds_read_b128 v[68:71], v49 offset:36864
	ds_read_b128 v[72:75], v42
	s_waitcnt lgkmcnt(4)
	v_mfma_f32_32x32x16_bf16 v[18:33], v[56:59], v[60:63], v[18:33]
	v_add_u32_e32 v42, -1, v54
	v_fma_f32 v49, -v42, v54, v38
	v_add_u32_e32 v55, 1, v54
	v_fma_f32 v56, -v55, v54, v38
	v_cmp_ge_f32_e64 s[4:5], 0, v49
	s_waitcnt lgkmcnt(2)
	v_mfma_f32_32x32x16_bf16 v[2:17], v[50:53], v[64:67], v[2:17]
	v_cndmask_b32_e64 v42, v54, v42, s[4:5]
	v_cmp_lt_f32_e64 s[4:5], 0, v56
	s_nop 1
	v_cndmask_b32_e64 v42, v42, v55, s[4:5]
	v_mul_f32_e32 v49, 0x37800000, v42
	v_cndmask_b32_e32 v42, v42, v49, vcc
	s_waitcnt lgkmcnt(1)
	v_mfma_f32_32x32x16_bf16 v[18:33], v[50:53], v[68:71], v[18:33]
	v_cmp_class_f32_e32 vcc, v38, v46
	ds_read_b128 v[50:53], v45 offset:32768
	ds_read_b128 v[54:57], v45 offset:36864
	v_cndmask_b32_e32 v38, v42, v38, vcc
	v_div_scale_f32 v42, s[4:5], v38, v38, 1.0
	v_rcp_f32_e32 v49, v42
	s_waitcnt lgkmcnt(1)
	v_mfma_f32_32x32x16_bf16 v[2:17], v[72:75], v[50:53], v[2:17]
	v_fma_f32 v45, -v42, v49, 1.0
	v_fmac_f32_e32 v49, v45, v49
	v_div_scale_f32 v45, vcc, 1.0, v38, 1.0
	v_mul_f32_e32 v58, v45, v49
	v_fma_f32 v59, -v42, v58, v45
	s_waitcnt lgkmcnt(0)
	v_mfma_f32_32x32x16_bf16 v[18:33], v[72:75], v[54:57], v[18:33]
	v_fmac_f32_e32 v58, v59, v49
	v_fma_f32 v42, -v42, v58, v45
	v_div_fmas_f32 v42, v42, v49, v58
	v_div_fixup_f32 v38, v42, v38, 1.0
	s_nop 0
	v_mul_f32_e32 v2, v2, v38
	v_max_f32_e32 v2, 0, v2
	v_mul_f32_e32 v2, v2, v2
	s_nop 3
	v_mul_f32_e32 v18, v18, v38
	v_and_b32_e32 v38, 0xffffff00, v44
	v_add_u32_e32 v44, s25, v38
	v_lshlrev_b32_e32 v38, 6, v47
	v_and_or_b32 v38, v38, s23, v48
	v_lshlrev_b32_e32 v42, 1, v38
	v_bfe_u32 v38, v2, 16, 1
	v_add3_u32 v2, v2, v38, s24
	v_fmamk_f32 v38, v39, 0x39800000, v1
	v_mul_f32_e32 v39, 0x4f800000, v38
	v_cmp_gt_f32_e32 vcc, s22, v38
	v_ashrrev_i32_e32 v45, 31, v44
	v_lshlrev_b64 v[44:45], 15, v[44:45]
	v_cndmask_b32_e32 v38, v38, v39, vcc
	v_sqrt_f32_e32 v39, v38
	v_lshl_add_u64 v[44:45], s[10:11], 0, v[44:45]
	v_max_f32_e32 v18, 0, v18
	v_lshl_add_u64 v[44:45], v[44:45], 0, v[42:43]
	v_add_u32_e32 v48, -1, v39
	v_fma_f32 v49, -v48, v39, v38
	v_cmp_ge_f32_e64 s[4:5], 0, v49
	v_add_u32_e32 v49, 1, v39
	global_store_short_d16_hi v[44:45], v2, off
	v_cndmask_b32_e64 v48, v39, v48, s[4:5]
	v_fma_f32 v39, -v49, v39, v38
	v_cmp_lt_f32_e64 s[4:5], 0, v39
	v_mul_f32_e32 v2, v18, v18
	v_bfe_u32 v18, v2, 16, 1
	v_cndmask_b32_e64 v39, v48, v49, s[4:5]
	v_mul_f32_e32 v48, 0x37800000, v39
	v_cndmask_b32_e32 v39, v39, v48, vcc
	v_cmp_class_f32_e32 vcc, v38, v46
	v_add3_u32 v2, v2, v18, s24
	global_store_short_d16_hi v[44:45], v2, off offset:64
	v_cndmask_b32_e32 v38, v39, v38, vcc
	v_div_scale_f32 v39, s[4:5], v38, v38, 1.0
	v_rcp_f32_e32 v48, v39
	v_add_u32_e32 v2, 0x2001, v47
	v_and_b32_e32 v2, 0xffffff00, v2
	v_add_u32_e32 v2, s25, v2
	v_fma_f32 v18, -v39, v48, 1.0
	v_fmac_f32_e32 v48, v18, v48
	v_div_scale_f32 v18, vcc, 1.0, v38, 1.0
	v_mul_f32_e32 v44, v18, v48
	v_fma_f32 v45, -v39, v44, v18
	v_fmac_f32_e32 v44, v45, v48
	v_fma_f32 v18, -v39, v44, v18
	v_div_fmas_f32 v18, v18, v48, v44
	v_div_fixup_f32 v18, v18, v38, 1.0
	v_mul_f32_e32 v3, v3, v18
	v_max_f32_e32 v38, 0, v3
	v_mul_f32_e32 v3, v19, v18
	v_mul_f32_e32 v19, v38, v38
	v_bfe_u32 v38, v19, 16, 1
	v_add3_u32 v19, v19, v38, s24
	v_fmamk_f32 v38, v40, 0x39800000, v1
	v_mul_f32_e32 v39, 0x4f800000, v38
	v_cmp_gt_f32_e32 vcc, s22, v38
	v_max_f32_e32 v18, 0, v3
	v_ashrrev_i32_e32 v3, 31, v2
	v_cndmask_b32_e32 v38, v38, v39, vcc
	v_sqrt_f32_e32 v39, v38
	v_lshlrev_b64 v[2:3], 15, v[2:3]
	v_lshl_add_u64 v[2:3], s[10:11], 0, v[2:3]
	v_lshl_add_u64 v[2:3], v[2:3], 0, v[42:43]
	v_add_u32_e32 v40, -1, v39
	v_fma_f32 v44, -v40, v39, v38
	v_cmp_ge_f32_e64 s[4:5], 0, v44
	v_add_u32_e32 v44, 1, v39
	v_mul_f32_e32 v18, v18, v18
	v_cndmask_b32_e64 v40, v39, v40, s[4:5]
	v_fma_f32 v39, -v44, v39, v38
	v_cmp_lt_f32_e64 s[4:5], 0, v39
	global_store_short_d16_hi v[2:3], v19, off offset:128
	v_bfe_u32 v19, v18, 16, 1
	v_cndmask_b32_e64 v39, v40, v44, s[4:5]
	v_mul_f32_e32 v40, 0x37800000, v39
	v_cndmask_b32_e32 v39, v39, v40, vcc
	v_cmp_class_f32_e32 vcc, v38, v46
	v_add3_u32 v18, v18, v19, s24
	global_store_short_d16_hi v[2:3], v18, off offset:192
	v_cndmask_b32_e32 v38, v39, v38, vcc
	v_div_scale_f32 v39, s[4:5], v38, v38, 1.0
	v_rcp_f32_e32 v40, v39
	v_add_u32_e32 v2, 0x2002, v47
	v_and_b32_e32 v2, 0xffffff00, v2
	v_add_u32_e32 v2, s25, v2
	v_fma_f32 v3, -v39, v40, 1.0
	v_fmac_f32_e32 v40, v3, v40
	v_div_scale_f32 v3, vcc, 1.0, v38, 1.0
	v_mul_f32_e32 v18, v3, v40
	v_fma_f32 v19, -v39, v18, v3
	v_fmac_f32_e32 v18, v19, v40
	v_fma_f32 v3, -v39, v18, v3
	v_div_fmas_f32 v3, v3, v40, v18
	v_div_fixup_f32 v3, v3, v38, 1.0
	v_mul_f32_e32 v4, v4, v3
	v_max_f32_e32 v4, 0, v4
	v_mul_f32_e32 v4, v4, v4
	v_bfe_u32 v19, v4, 16, 1
	v_add3_u32 v4, v4, v19, s24
	v_fmamk_f32 v19, v41, 0x39800000, v1
	v_mul_f32_e32 v3, v20, v3
	v_mul_f32_e32 v20, 0x4f800000, v19
	v_cmp_gt_f32_e32 vcc, s22, v19
	v_max_f32_e32 v18, 0, v3
	v_ashrrev_i32_e32 v3, 31, v2
	v_cndmask_b32_e32 v19, v19, v20, vcc
	v_sqrt_f32_e32 v20, v19
	v_lshlrev_b64 v[2:3], 15, v[2:3]
	v_lshl_add_u64 v[2:3], s[10:11], 0, v[2:3]
	v_lshl_add_u64 v[2:3], v[2:3], 0, v[42:43]
	v_add_u32_e32 v38, -1, v20
	v_fma_f32 v39, -v38, v20, v19
	v_cmp_ge_f32_e64 s[4:5], 0, v39
	v_add_u32_e32 v39, 1, v20
	global_store_short_d16_hi v[2:3], v4, off offset:256
	v_cndmask_b32_e64 v38, v20, v38, s[4:5]
	v_fma_f32 v20, -v39, v20, v19
	v_cmp_lt_f32_e64 s[4:5], 0, v20
	v_mul_f32_e32 v4, v18, v18
	v_bfe_u32 v18, v4, 16, 1
	v_cndmask_b32_e64 v20, v38, v39, s[4:5]
	v_mul_f32_e32 v38, 0x37800000, v20
	v_cndmask_b32_e32 v20, v20, v38, vcc
	v_cmp_class_f32_e32 vcc, v19, v46
	v_add3_u32 v4, v4, v18, s24
	global_store_short_d16_hi v[2:3], v4, off offset:320
	v_cndmask_b32_e32 v19, v20, v19, vcc
	v_div_scale_f32 v20, s[4:5], v19, v19, 1.0
	v_rcp_f32_e32 v38, v20
	v_add_u32_e32 v2, 0x2003, v47
	v_and_b32_e32 v2, 0xffffff00, v2
	v_add_u32_e32 v2, s25, v2
	v_fma_f32 v3, -v20, v38, 1.0
	v_fmac_f32_e32 v38, v3, v38
	v_div_scale_f32 v3, vcc, 1.0, v19, 1.0
	v_mul_f32_e32 v4, v3, v38
	v_fma_f32 v18, -v20, v4, v3
	v_fmac_f32_e32 v4, v18, v38
	v_fma_f32 v3, -v20, v4, v3
	v_div_fmas_f32 v3, v3, v38, v4
	v_div_fixup_f32 v3, v3, v19, 1.0
	v_fmamk_f32 v19, v34, 0x39800000, v1
	v_mul_f32_e32 v20, 0x4f800000, v19
	v_cmp_gt_f32_e32 vcc, s22, v19
	v_mul_f32_e32 v4, v5, v3
	v_mul_f32_e32 v3, v21, v3
	v_cndmask_b32_e32 v19, v19, v20, vcc
	v_max_f32_e32 v4, 0, v4
	v_max_f32_e32 v5, 0, v3
	v_ashrrev_i32_e32 v3, 31, v2
	v_sqrt_f32_e32 v20, v19
	v_lshlrev_b64 v[2:3], 15, v[2:3]
	v_mul_f32_e32 v4, v4, v4
	v_lshl_add_u64 v[2:3], s[10:11], 0, v[2:3]
	v_bfe_u32 v18, v4, 16, 1
	v_lshl_add_u64 v[2:3], v[2:3], 0, v[42:43]
	v_add3_u32 v4, v4, v18, s24
	global_store_short_d16_hi v[2:3], v4, off offset:384
	v_mul_f32_e32 v4, v5, v5
	v_add_u32_e32 v5, -1, v20
	v_fma_f32 v18, -v5, v20, v19
	v_cmp_ge_f32_e64 s[4:5], 0, v18
	v_add_u32_e32 v18, 1, v20
	s_nop 0
	v_cndmask_b32_e64 v5, v20, v5, s[4:5]
	v_fma_f32 v20, -v18, v20, v19
	v_cmp_lt_f32_e64 s[4:5], 0, v20
	v_bfe_u32 v20, v4, 16, 1
	v_add3_u32 v4, v4, v20, s24
	v_cndmask_b32_e64 v5, v5, v18, s[4:5]
	v_mul_f32_e32 v18, 0x37800000, v5
	v_cndmask_b32_e32 v5, v5, v18, vcc
	v_cmp_class_f32_e32 vcc, v19, v46
	global_store_short_d16_hi v[2:3], v4, off offset:448
	s_nop 0
	v_cndmask_b32_e32 v5, v5, v19, vcc
	v_div_scale_f32 v18, s[4:5], v5, v5, 1.0
	v_rcp_f32_e32 v19, v18
	s_nop 0
	v_fma_f32 v2, -v18, v19, 1.0
	v_fmac_f32_e32 v19, v2, v19
	v_div_scale_f32 v2, vcc, 1.0, v5, 1.0
	v_mul_f32_e32 v3, v2, v19
	v_fma_f32 v4, -v18, v3, v2
	v_fmac_f32_e32 v3, v4, v19
	v_fma_f32 v2, -v18, v3, v2
	v_div_fmas_f32 v2, v2, v19, v3
	v_div_fixup_f32 v2, v2, v5, 1.0
	v_mul_f32_e32 v3, v6, v2
	v_max_f32_e32 v4, 0, v3
	v_mul_f32_e32 v4, v4, v4
	v_bfe_u32 v6, v4, 16, 1
	v_add3_u32 v4, v4, v6, s24
	v_fmamk_f32 v6, v35, 0x39800000, v1
	v_mul_f32_e32 v18, 0x4f800000, v6
	v_cmp_gt_f32_e32 vcc, s22, v6
	v_mul_f32_e32 v2, v22, v2
	v_max_f32_e32 v5, 0, v2
	v_cndmask_b32_e32 v6, v6, v18, vcc
	v_sqrt_f32_e32 v18, v6
	v_and_b32_e32 v2, 0xffffff00, v76
	v_add_u32_e32 v2, s25, v2
	v_ashrrev_i32_e32 v3, 31, v2
	v_add_u32_e32 v19, -1, v18
	v_fma_f32 v20, -v19, v18, v6
	v_cmp_ge_f32_e64 s[4:5], 0, v20
	v_add_u32_e32 v20, 1, v18
	v_lshlrev_b64 v[2:3], 15, v[2:3]
	v_cndmask_b32_e64 v19, v18, v19, s[4:5]
	v_fma_f32 v18, -v20, v18, v6
	v_cmp_lt_f32_e64 s[4:5], 0, v18
	v_lshl_add_u64 v[2:3], s[10:11], 0, v[2:3]
	v_lshl_add_u64 v[2:3], v[2:3], 0, v[42:43]
	v_cndmask_b32_e64 v18, v19, v20, s[4:5]
	v_mul_f32_e32 v19, 0x37800000, v18
	v_cndmask_b32_e32 v18, v18, v19, vcc
	v_cmp_class_f32_e32 vcc, v6, v46
	global_store_short_d16_hi v[2:3], v4, off offset:1024
	v_mul_f32_e32 v4, v5, v5
	v_cndmask_b32_e32 v6, v18, v6, vcc
	v_div_scale_f32 v18, s[4:5], v6, v6, 1.0
	v_rcp_f32_e32 v19, v18
	v_bfe_u32 v5, v4, 16, 1
	v_add3_u32 v4, v4, v5, s24
	global_store_short_d16_hi v[2:3], v4, off offset:1088
	v_fma_f32 v3, -v18, v19, 1.0
	v_fmac_f32_e32 v19, v3, v19
	v_div_scale_f32 v3, vcc, 1.0, v6, 1.0
	v_mul_f32_e32 v4, v3, v19
	v_fma_f32 v5, -v18, v4, v3
	v_fmac_f32_e32 v4, v5, v19
	v_fma_f32 v3, -v18, v4, v3
	v_add_u32_e32 v2, 0x2009, v47
	v_div_fmas_f32 v3, v3, v19, v4
	v_div_fixup_f32 v3, v3, v6, 1.0
	v_and_b32_e32 v2, 0xffffff00, v2
	v_mul_f32_e32 v4, v7, v3
	v_mul_f32_e32 v3, v23, v3
	v_add_u32_e32 v2, s25, v2
	v_max_f32_e32 v5, 0, v3
	v_ashrrev_i32_e32 v3, 31, v2
	v_lshlrev_b64 v[2:3], 15, v[2:3]
	v_max_f32_e32 v4, 0, v4
	v_lshl_add_u64 v[2:3], s[10:11], 0, v[2:3]
	v_lshl_add_u64 v[6:7], v[2:3], 0, v[42:43]
	v_mul_f32_e32 v2, v4, v4
	v_bfe_u32 v3, v2, 16, 1
	v_add3_u32 v2, v2, v3, s24
	global_store_short_d16_hi v[6:7], v2, off offset:1152
	v_fmamk_f32 v2, v36, 0x39800000, v1
	v_mul_f32_e32 v3, 0x4f800000, v2
	v_cmp_gt_f32_e32 vcc, s22, v2
	v_mul_f32_e32 v4, v5, v5
	v_bfe_u32 v5, v4, 16, 1
	v_cndmask_b32_e32 v2, v2, v3, vcc
	v_sqrt_f32_e32 v3, v2
	v_add3_u32 v20, v4, v5, s24
	v_add_u32_e32 v18, 0x2010, v47
	v_ashrrev_i32_e32 v19, 31, v18
	v_add_u32_e32 v4, -1, v3
	v_fma_f32 v5, -v4, v3, v2
	v_cmp_ge_f32_e64 s[4:5], 0, v5
	v_add_u32_e32 v5, 1, v3
	global_store_short_d16_hi v[6:7], v20, off offset:1216
	v_cndmask_b32_e64 v4, v3, v4, s[4:5]
	v_fma_f32 v3, -v5, v3, v2
	v_cmp_lt_f32_e64 s[4:5], 0, v3
	v_add_u32_e32 v6, 0x200a, v47
	v_and_b32_e32 v6, 0xffffff00, v6
	v_cndmask_b32_e64 v3, v4, v5, s[4:5]
	v_mul_f32_e32 v4, 0x37800000, v3
	v_cndmask_b32_e32 v3, v3, v4, vcc
	v_cmp_class_f32_e32 vcc, v2, v46
	v_add_u32_e32 v6, s25, v6
	s_nop 0
	v_cndmask_b32_e32 v21, v3, v2, vcc
	v_lshl_add_u64 v[2:3], v[18:19], 2, s[8:9]
	global_load_dwordx4 v[2:5], v[2:3], off
	v_div_scale_f32 v22, s[4:5], v21, v21, 1.0
	v_rcp_f32_e32 v23, v22
	v_and_b32_e32 v18, 0xffffff00, v18
	v_add_u32_e32 v18, s25, v18
	v_fma_f32 v7, -v22, v23, 1.0
	v_fmac_f32_e32 v23, v7, v23
	v_div_scale_f32 v7, vcc, 1.0, v21, 1.0
	v_mul_f32_e32 v19, v7, v23
	v_fma_f32 v20, -v22, v19, v7
	v_fmac_f32_e32 v19, v20, v23
	v_fma_f32 v7, -v22, v19, v7
	v_div_fmas_f32 v7, v7, v23, v19
	v_div_fixup_f32 v7, v7, v21, 1.0
	v_mul_f32_e32 v8, v8, v7
	v_max_f32_e32 v8, 0, v8
	v_mul_f32_e32 v8, v8, v8
	v_bfe_u32 v20, v8, 16, 1
	v_add3_u32 v8, v8, v20, s24
	v_fmamk_f32 v20, v37, 0x39800000, v1
	v_mul_f32_e32 v21, 0x4f800000, v20
	v_cmp_gt_f32_e32 vcc, s22, v20
	v_mul_f32_e32 v7, v24, v7
	v_max_f32_e32 v19, 0, v7
	v_cndmask_b32_e32 v20, v20, v21, vcc
	v_sqrt_f32_e32 v21, v20
	v_ashrrev_i32_e32 v7, 31, v6
	v_lshlrev_b64 v[6:7], 15, v[6:7]
	v_lshl_add_u64 v[6:7], s[10:11], 0, v[6:7]
	v_add_u32_e32 v22, -1, v21
	v_fma_f32 v23, -v22, v21, v20
	v_cmp_ge_f32_e64 s[4:5], 0, v23
	v_add_u32_e32 v23, 1, v21
	v_lshl_add_u64 v[6:7], v[6:7], 0, v[42:43]
	v_cndmask_b32_e64 v22, v21, v22, s[4:5]
	v_fma_f32 v21, -v23, v21, v20
	v_cmp_lt_f32_e64 s[4:5], 0, v21
	global_store_short_d16_hi v[6:7], v8, off offset:1280
	v_mul_f32_e32 v8, v19, v19
	v_cndmask_b32_e64 v21, v22, v23, s[4:5]
	v_mul_f32_e32 v22, 0x37800000, v21
	v_cndmask_b32_e32 v21, v21, v22, vcc
	v_cmp_class_f32_e32 vcc, v20, v46
	v_bfe_u32 v19, v8, 16, 1
	v_add3_u32 v8, v8, v19, s24
	v_cndmask_b32_e32 v20, v21, v20, vcc
	v_div_scale_f32 v21, s[4:5], v20, v20, 1.0
	v_rcp_f32_e32 v22, v21
	global_store_short_d16_hi v[6:7], v8, off offset:1344
	v_add_u32_e32 v6, 0x200b, v47
	v_and_b32_e32 v6, 0xffffff00, v6
	v_fma_f32 v7, -v21, v22, 1.0
	v_fmac_f32_e32 v22, v7, v22
	v_div_scale_f32 v7, vcc, 1.0, v20, 1.0
	v_mul_f32_e32 v8, v7, v22
	v_fma_f32 v19, -v21, v8, v7
	v_fmac_f32_e32 v8, v19, v22
	v_fma_f32 v7, -v21, v8, v7
	v_div_fmas_f32 v7, v7, v22, v8
	v_div_fixup_f32 v7, v7, v20, 1.0
	v_mul_f32_e32 v8, v9, v7
	v_mul_f32_e32 v7, v25, v7
	v_add_u32_e32 v6, s25, v6
	v_max_f32_e32 v19, 0, v7
	v_ashrrev_i32_e32 v7, 31, v6
	v_lshlrev_b64 v[6:7], 15, v[6:7]
	v_add_u32_e32 v22, 0x2018, v47
	v_lshl_add_u64 v[6:7], s[10:11], 0, v[6:7]
	v_ashrrev_i32_e32 v23, 31, v22
	v_max_f32_e32 v8, 0, v8
	v_lshl_add_u64 v[20:21], v[6:7], 0, v[42:43]
	v_lshl_add_u64 v[6:7], v[22:23], 2, s[8:9]
	v_mul_f32_e32 v24, v8, v8
	global_load_dwordx4 v[6:9], v[6:7], off
	v_bfe_u32 v25, v24, 16, 1
	s_waitcnt vmcnt(3)
	v_fmamk_f32 v2, v2, 0x39800000, v1
	v_mul_f32_e32 v23, 0x4f800000, v2
	v_cmp_gt_f32_e32 vcc, s22, v2
	v_add3_u32 v24, v24, v25, s24
	global_store_short_d16_hi v[20:21], v24, off offset:1408
	v_cndmask_b32_e32 v2, v2, v23, vcc
	v_sqrt_f32_e32 v23, v2
	v_mul_f32_e32 v19, v19, v19
	v_fmamk_f32 v3, v3, 0x39800000, v1
	v_fmamk_f32 v4, v4, 0x39800000, v1
	v_add_u32_e32 v24, -1, v23
	v_fma_f32 v25, -v24, v23, v2
	v_cmp_ge_f32_e64 s[4:5], 0, v25
	v_add_u32_e32 v25, 1, v23
	v_fmamk_f32 v5, v5, 0x39800000, v1
	v_cndmask_b32_e64 v24, v23, v24, s[4:5]
	v_fma_f32 v23, -v25, v23, v2
	v_cmp_lt_f32_e64 s[4:5], 0, v23
	s_waitcnt vmcnt(1)
	v_fmamk_f32 v6, v6, 0x39800000, v1
	v_cndmask_b32_e64 v23, v24, v25, s[4:5]
	v_mul_f32_e32 v24, 0x37800000, v23
	v_cndmask_b32_e32 v23, v23, v24, vcc
	v_cmp_class_f32_e32 vcc, v2, v46
	v_bfe_u32 v25, v19, 16, 1
	v_add3_u32 v19, v19, v25, s24
	v_cndmask_b32_e32 v2, v23, v2, vcc
	v_div_scale_f32 v23, s[4:5], v2, v2, 1.0
	v_rcp_f32_e32 v24, v23
	global_store_short_d16_hi v[20:21], v19, off offset:1472
	v_fma_f32 v19, -v23, v24, 1.0
	v_fmac_f32_e32 v24, v19, v24
	v_div_scale_f32 v19, vcc, 1.0, v2, 1.0
	v_mul_f32_e32 v20, v19, v24
	v_fma_f32 v21, -v23, v20, v19
	v_fmac_f32_e32 v20, v21, v24
	v_fma_f32 v19, -v23, v20, v19
	v_div_fmas_f32 v19, v19, v24, v20
	v_div_fixup_f32 v2, v19, v2, 1.0
	v_mul_f32_e32 v10, v10, v2
	v_max_f32_e32 v10, 0, v10
	v_mul_f32_e32 v10, v10, v10
	v_bfe_u32 v20, v10, 16, 1
	v_add3_u32 v10, v10, v20, s24
	v_mul_f32_e32 v20, 0x4f800000, v3
	v_cmp_gt_f32_e32 vcc, s22, v3
	v_ashrrev_i32_e32 v19, 31, v18
	v_mul_f32_e32 v2, v26, v2
	v_cndmask_b32_e32 v3, v3, v20, vcc
	v_sqrt_f32_e32 v20, v3
	v_lshlrev_b64 v[18:19], 15, v[18:19]
	v_max_f32_e32 v2, 0, v2
	v_lshl_add_u64 v[18:19], s[10:11], 0, v[18:19]
	v_add_u32_e32 v21, -1, v20
	v_fma_f32 v23, -v21, v20, v3
	v_cmp_ge_f32_e64 s[4:5], 0, v23
	v_add_u32_e32 v23, 1, v20
	v_lshl_add_u64 v[18:19], v[18:19], 0, v[42:43]
	v_cndmask_b32_e64 v21, v20, v21, s[4:5]
	v_fma_f32 v20, -v23, v20, v3
	v_cmp_lt_f32_e64 s[4:5], 0, v20
	v_mul_f32_e32 v2, v2, v2
	global_store_short_d16_hi v[18:19], v10, off offset:2048
	v_cndmask_b32_e64 v20, v21, v23, s[4:5]
	v_mul_f32_e32 v21, 0x37800000, v20
	v_cndmask_b32_e32 v20, v20, v21, vcc
	v_cmp_class_f32_e32 vcc, v3, v46
	v_bfe_u32 v10, v2, 16, 1
	v_add3_u32 v2, v2, v10, s24
	v_cndmask_b32_e32 v3, v20, v3, vcc
	v_div_scale_f32 v20, s[4:5], v3, v3, 1.0
	v_rcp_f32_e32 v21, v20
	global_store_short_d16_hi v[18:19], v2, off offset:2112
	v_add_u32_e32 v2, 0x2011, v47
	v_and_b32_e32 v2, 0xffffff00, v2
	v_fma_f32 v10, -v20, v21, 1.0
	v_fmac_f32_e32 v21, v10, v21
	v_div_scale_f32 v10, vcc, 1.0, v3, 1.0
	v_mul_f32_e32 v18, v10, v21
	v_fma_f32 v19, -v20, v18, v10
	v_fmac_f32_e32 v18, v19, v21
	v_fma_f32 v10, -v20, v18, v10
	v_div_fmas_f32 v10, v10, v21, v18
	v_div_fixup_f32 v3, v10, v3, 1.0
	v_mul_f32_e32 v10, v11, v3
	v_max_f32_e32 v10, 0, v10
	v_mul_f32_e32 v10, v10, v10
	v_bfe_u32 v18, v10, 16, 1
	v_add3_u32 v10, v10, v18, s24
	v_mul_f32_e32 v18, 0x4f800000, v4
	v_cmp_gt_f32_e32 vcc, s22, v4
	v_mul_f32_e32 v3, v27, v3
	v_add_u32_e32 v2, s25, v2
	v_cndmask_b32_e32 v4, v4, v18, vcc
	v_sqrt_f32_e32 v18, v4
	v_max_f32_e32 v11, 0, v3
	v_ashrrev_i32_e32 v3, 31, v2
	v_lshlrev_b64 v[2:3], 15, v[2:3]
	v_add_u32_e32 v19, -1, v18
	v_fma_f32 v20, -v19, v18, v4
	v_cmp_ge_f32_e64 s[4:5], 0, v20
	v_add_u32_e32 v20, 1, v18
	v_lshl_add_u64 v[2:3], s[10:11], 0, v[2:3]
	v_cndmask_b32_e64 v19, v18, v19, s[4:5]
	v_fma_f32 v18, -v20, v18, v4
	v_cmp_lt_f32_e64 s[4:5], 0, v18
	v_lshl_add_u64 v[2:3], v[2:3], 0, v[42:43]
	global_store_short_d16_hi v[2:3], v10, off offset:2176
	v_cndmask_b32_e64 v18, v19, v20, s[4:5]
	v_mul_f32_e32 v19, 0x37800000, v18
	v_cndmask_b32_e32 v18, v18, v19, vcc
	v_cmp_class_f32_e32 vcc, v4, v46
	v_mul_f32_e32 v10, v11, v11
	v_bfe_u32 v11, v10, 16, 1
	v_cndmask_b32_e32 v4, v18, v4, vcc
	v_div_scale_f32 v18, s[4:5], v4, v4, 1.0
	v_rcp_f32_e32 v19, v18
	v_add3_u32 v10, v10, v11, s24
	global_store_short_d16_hi v[2:3], v10, off offset:2240
	v_add_u32_e32 v2, 0x2012, v47
	v_fma_f32 v3, -v18, v19, 1.0
	v_fmac_f32_e32 v19, v3, v19
	v_div_scale_f32 v3, vcc, 1.0, v4, 1.0
	v_mul_f32_e32 v10, v3, v19
	v_fma_f32 v11, -v18, v10, v3
	v_fmac_f32_e32 v10, v11, v19
	v_fma_f32 v3, -v18, v10, v3
	v_div_fmas_f32 v3, v3, v19, v10
	v_div_fixup_f32 v3, v3, v4, 1.0
	v_mul_f32_e32 v4, v12, v3
	v_max_f32_e32 v4, 0, v4
	v_mul_f32_e32 v4, v4, v4
	v_bfe_u32 v11, v4, 16, 1
	v_add3_u32 v4, v4, v11, s24
	v_mul_f32_e32 v11, 0x4f800000, v5
	v_cmp_gt_f32_e32 vcc, s22, v5
	v_and_b32_e32 v2, 0xffffff00, v2
	v_mul_f32_e32 v3, v28, v3
	v_cndmask_b32_e32 v5, v5, v11, vcc
	v_sqrt_f32_e32 v11, v5
	v_add_u32_e32 v2, s25, v2
	v_max_f32_e32 v10, 0, v3
	v_ashrrev_i32_e32 v3, 31, v2
	v_add_u32_e32 v12, -1, v11
	v_fma_f32 v18, -v12, v11, v5
	v_cmp_ge_f32_e64 s[4:5], 0, v18
	v_add_u32_e32 v18, 1, v11
	v_lshlrev_b64 v[2:3], 15, v[2:3]
	v_cndmask_b32_e64 v12, v11, v12, s[4:5]
	v_fma_f32 v11, -v18, v11, v5
	v_cmp_lt_f32_e64 s[4:5], 0, v11
	v_lshl_add_u64 v[2:3], s[10:11], 0, v[2:3]
	v_lshl_add_u64 v[2:3], v[2:3], 0, v[42:43]
	v_cndmask_b32_e64 v11, v12, v18, s[4:5]
	v_mul_f32_e32 v12, 0x37800000, v11
	v_cndmask_b32_e32 v11, v11, v12, vcc
	v_cmp_class_f32_e32 vcc, v5, v46
	global_store_short_d16_hi v[2:3], v4, off offset:2304
	v_mul_f32_e32 v4, v10, v10
	v_cndmask_b32_e32 v5, v11, v5, vcc
	v_div_scale_f32 v11, s[4:5], v5, v5, 1.0
	v_rcp_f32_e32 v12, v11
	v_bfe_u32 v10, v4, 16, 1
	v_add3_u32 v4, v4, v10, s24
	global_store_short_d16_hi v[2:3], v4, off offset:2368
	v_fma_f32 v3, -v11, v12, 1.0
	v_fmac_f32_e32 v12, v3, v12
	v_div_scale_f32 v3, vcc, 1.0, v5, 1.0
	v_mul_f32_e32 v4, v3, v12
	v_fma_f32 v10, -v11, v4, v3
	v_fmac_f32_e32 v4, v10, v12
	v_fma_f32 v3, -v11, v4, v3
	v_add_u32_e32 v2, 0x2013, v47
	v_div_fmas_f32 v3, v3, v12, v4
	v_div_fixup_f32 v3, v3, v5, 1.0
	v_and_b32_e32 v2, 0xffffff00, v2
	v_mul_f32_e32 v11, 0x4f800000, v6
	v_cmp_gt_f32_e32 vcc, s22, v6
	v_mul_f32_e32 v4, v13, v3
	v_mul_f32_e32 v3, v29, v3
	v_add_u32_e32 v2, s25, v2
	v_cndmask_b32_e32 v6, v6, v11, vcc
	v_max_f32_e32 v4, 0, v4
	v_max_f32_e32 v5, 0, v3
	v_ashrrev_i32_e32 v3, 31, v2
	v_sqrt_f32_e32 v11, v6
	v_lshlrev_b64 v[2:3], 15, v[2:3]
	v_mul_f32_e32 v4, v4, v4
	v_lshl_add_u64 v[2:3], s[10:11], 0, v[2:3]
	v_bfe_u32 v10, v4, 16, 1
	v_lshl_add_u64 v[2:3], v[2:3], 0, v[42:43]
	v_add3_u32 v4, v4, v10, s24
	global_store_short_d16_hi v[2:3], v4, off offset:2432
	v_mul_f32_e32 v4, v5, v5
	v_add_u32_e32 v5, -1, v11
	v_fma_f32 v10, -v5, v11, v6
	v_cmp_ge_f32_e64 s[4:5], 0, v10
	v_add_u32_e32 v10, 1, v11
	s_nop 0
	v_cndmask_b32_e64 v5, v11, v5, s[4:5]
	v_fma_f32 v11, -v10, v11, v6
	v_cmp_lt_f32_e64 s[4:5], 0, v11
	v_bfe_u32 v11, v4, 16, 1
	v_add3_u32 v4, v4, v11, s24
	v_cndmask_b32_e64 v5, v5, v10, s[4:5]
	v_mul_f32_e32 v10, 0x37800000, v5
	v_cndmask_b32_e32 v5, v5, v10, vcc
	v_cmp_class_f32_e32 vcc, v6, v46
	global_store_short_d16_hi v[2:3], v4, off offset:2496
	s_nop 0
	v_cndmask_b32_e32 v5, v5, v6, vcc
	v_div_scale_f32 v6, s[4:5], v5, v5, 1.0
	v_rcp_f32_e32 v10, v6
	s_nop 0
	v_fma_f32 v2, -v6, v10, 1.0
	v_fmac_f32_e32 v10, v2, v10
	v_div_scale_f32 v2, vcc, 1.0, v5, 1.0
	v_mul_f32_e32 v3, v2, v10
	v_fma_f32 v4, -v6, v3, v2
	v_fmac_f32_e32 v3, v4, v10
	v_fma_f32 v2, -v6, v3, v2
	v_div_fmas_f32 v2, v2, v10, v3
	v_div_fixup_f32 v2, v2, v5, 1.0
	v_mul_f32_e32 v3, v14, v2
	v_max_f32_e32 v4, 0, v3
	v_mul_f32_e32 v4, v4, v4
	v_bfe_u32 v6, v4, 16, 1
	v_add3_u32 v4, v4, v6, s24
	v_fmamk_f32 v6, v7, 0x39800000, v1
	v_mul_f32_e32 v7, 0x4f800000, v6
	v_cmp_gt_f32_e32 vcc, s22, v6
	v_mul_f32_e32 v2, v30, v2
	v_max_f32_e32 v5, 0, v2
	v_cndmask_b32_e32 v6, v6, v7, vcc
	v_sqrt_f32_e32 v7, v6
	v_and_b32_e32 v2, 0xffffff00, v22
	v_add_u32_e32 v2, s25, v2
	v_ashrrev_i32_e32 v3, 31, v2
	v_add_u32_e32 v10, -1, v7
	v_fma_f32 v11, -v10, v7, v6
	v_cmp_ge_f32_e64 s[4:5], 0, v11
	v_add_u32_e32 v11, 1, v7
	v_lshlrev_b64 v[2:3], 15, v[2:3]
	v_cndmask_b32_e64 v10, v7, v10, s[4:5]
	v_fma_f32 v7, -v11, v7, v6
	v_cmp_lt_f32_e64 s[4:5], 0, v7
	v_lshl_add_u64 v[2:3], s[10:11], 0, v[2:3]
	v_lshl_add_u64 v[2:3], v[2:3], 0, v[42:43]
	v_cndmask_b32_e64 v7, v10, v11, s[4:5]
	v_mul_f32_e32 v10, 0x37800000, v7
	v_cndmask_b32_e32 v7, v7, v10, vcc
	v_cmp_class_f32_e32 vcc, v6, v46
	global_store_short_d16_hi v[2:3], v4, off offset:3072
	v_mul_f32_e32 v4, v5, v5
	v_cndmask_b32_e32 v6, v7, v6, vcc
	v_div_scale_f32 v7, s[4:5], v6, v6, 1.0
	v_rcp_f32_e32 v10, v7
	v_bfe_u32 v5, v4, 16, 1
	v_add3_u32 v4, v4, v5, s24
	global_store_short_d16_hi v[2:3], v4, off offset:3136
	v_fma_f32 v3, -v7, v10, 1.0
	v_fmac_f32_e32 v10, v3, v10
	v_div_scale_f32 v3, vcc, 1.0, v6, 1.0
	v_mul_f32_e32 v4, v3, v10
	v_fma_f32 v5, -v7, v4, v3
	v_fmac_f32_e32 v4, v5, v10
	v_fma_f32 v3, -v7, v4, v3
	v_div_fmas_f32 v3, v3, v10, v4
	v_div_fixup_f32 v3, v3, v6, 1.0
	v_mul_f32_e32 v4, v15, v3
	v_max_f32_e32 v4, 0, v4
	v_mul_f32_e32 v4, v4, v4
	v_bfe_u32 v6, v4, 16, 1
	v_add3_u32 v4, v4, v6, s24
	v_fmamk_f32 v6, v8, 0x39800000, v1
	v_mul_f32_e32 v7, 0x4f800000, v6
	v_cmp_gt_f32_e32 vcc, s22, v6
	v_add_u32_e32 v2, 0x2019, v47
	v_and_b32_e32 v2, 0xffffff00, v2
	v_cndmask_b32_e32 v6, v6, v7, vcc
	v_sqrt_f32_e32 v7, v6
	v_mul_f32_e32 v3, v31, v3
	v_add_u32_e32 v2, s25, v2
	v_max_f32_e32 v5, 0, v3
	v_add_u32_e32 v8, -1, v7
	v_fma_f32 v10, -v8, v7, v6
	v_cmp_ge_f32_e64 s[4:5], 0, v10
	v_add_u32_e32 v10, 1, v7
	v_ashrrev_i32_e32 v3, 31, v2
	v_cndmask_b32_e64 v8, v7, v8, s[4:5]
	v_fma_f32 v7, -v10, v7, v6
	v_cmp_lt_f32_e64 s[4:5], 0, v7
	v_lshlrev_b64 v[2:3], 15, v[2:3]
	v_lshl_add_u64 v[2:3], s[10:11], 0, v[2:3]
	v_cndmask_b32_e64 v7, v8, v10, s[4:5]
	v_mul_f32_e32 v8, 0x37800000, v7
	v_cndmask_b32_e32 v7, v7, v8, vcc
	v_cmp_class_f32_e32 vcc, v6, v46
	v_lshl_add_u64 v[2:3], v[2:3], 0, v[42:43]
	global_store_short_d16_hi v[2:3], v4, off offset:3200
	v_cndmask_b32_e32 v6, v7, v6, vcc
	v_div_scale_f32 v7, s[4:5], v6, v6, 1.0
	v_rcp_f32_e32 v8, v7
	v_mul_f32_e32 v4, v5, v5
	v_bfe_u32 v5, v4, 16, 1
	v_add3_u32 v4, v4, v5, s24
	global_store_short_d16_hi v[2:3], v4, off offset:3264
	v_fma_f32 v3, -v7, v8, 1.0
	v_fmac_f32_e32 v8, v3, v8
	v_div_scale_f32 v3, vcc, 1.0, v6, 1.0
	v_mul_f32_e32 v4, v3, v8
	v_fma_f32 v5, -v7, v4, v3
	v_fmac_f32_e32 v4, v5, v8
	v_fma_f32 v3, -v7, v4, v3
	v_div_fmas_f32 v3, v3, v8, v4
	v_div_fixup_f32 v3, v3, v6, 1.0
	v_mul_f32_e32 v4, v16, v3
	v_max_f32_e32 v4, 0, v4
	v_mul_f32_e32 v4, v4, v4
	v_bfe_u32 v6, v4, 16, 1
	v_add3_u32 v4, v4, v6, s24
	v_fmamk_f32 v6, v9, 0x39800000, v1
	v_mul_f32_e32 v7, 0x4f800000, v6
	v_cmp_gt_f32_e32 vcc, s22, v6
	v_add_u32_e32 v2, 0x201a, v47
	v_and_b32_e32 v2, 0xffffff00, v2
	v_cndmask_b32_e32 v6, v6, v7, vcc
	v_sqrt_f32_e32 v7, v6
	v_mul_f32_e32 v3, v32, v3
	v_add_u32_e32 v2, s25, v2
	v_max_f32_e32 v5, 0, v3
	v_add_u32_e32 v8, -1, v7
	v_fma_f32 v9, -v8, v7, v6
	v_cmp_ge_f32_e64 s[4:5], 0, v9
	v_add_u32_e32 v9, 1, v7
	v_ashrrev_i32_e32 v3, 31, v2
	v_cndmask_b32_e64 v8, v7, v8, s[4:5]
	v_fma_f32 v7, -v9, v7, v6
	v_cmp_lt_f32_e64 s[4:5], 0, v7
	v_lshlrev_b64 v[2:3], 15, v[2:3]
	v_lshl_add_u64 v[2:3], s[10:11], 0, v[2:3]
	v_cndmask_b32_e64 v7, v8, v9, s[4:5]
	v_mul_f32_e32 v8, 0x37800000, v7
	v_cndmask_b32_e32 v7, v7, v8, vcc
	v_cmp_class_f32_e32 vcc, v6, v46
	v_lshl_add_u64 v[2:3], v[2:3], 0, v[42:43]
	global_store_short_d16_hi v[2:3], v4, off offset:3328
	v_cndmask_b32_e32 v6, v7, v6, vcc
	v_div_scale_f32 v7, s[4:5], v6, v6, 1.0
	v_rcp_f32_e32 v8, v7
	v_mul_f32_e32 v4, v5, v5
	v_bfe_u32 v5, v4, 16, 1
	v_add3_u32 v4, v4, v5, s24
	global_store_short_d16_hi v[2:3], v4, off offset:3392
	v_fma_f32 v3, -v7, v8, 1.0
	v_fmac_f32_e32 v8, v3, v8
	v_div_scale_f32 v3, vcc, 1.0, v6, 1.0
	v_mul_f32_e32 v4, v3, v8
	v_fma_f32 v5, -v7, v4, v3
	v_fmac_f32_e32 v4, v5, v8
	v_fma_f32 v3, -v7, v4, v3
	v_add_u32_e32 v2, 0x201b, v47
	v_div_fmas_f32 v3, v3, v8, v4
	v_div_fixup_f32 v3, v3, v6, 1.0
	v_and_b32_e32 v2, 0xffffff00, v2
	v_mul_f32_e32 v4, v17, v3
	v_mul_f32_e32 v3, v33, v3
	v_add_u32_e32 v2, s25, v2
	v_max_f32_e32 v4, 0, v4
	v_max_f32_e32 v5, 0, v3
	v_ashrrev_i32_e32 v3, 31, v2
	v_lshlrev_b64 v[2:3], 15, v[2:3]
	v_mul_f32_e32 v4, v4, v4
	v_lshl_add_u64 v[2:3], s[10:11], 0, v[2:3]
	v_bfe_u32 v6, v4, 16, 1
	v_lshl_add_u64 v[2:3], v[2:3], 0, v[42:43]
	v_add3_u32 v4, v4, v6, s24
	global_store_short_d16_hi v[2:3], v4, off offset:3456
	v_mul_f32_e32 v4, v5, v5
	v_bfe_u32 v5, v4, 16, 1
	v_add3_u32 v4, v4, v5, s24
	global_store_short_d16_hi v[2:3], v4, off offset:3520
	s_waitcnt lgkmcnt(0)
	s_add_i32 s25, s25, s93
	s_cmpk_lt_i32 s25, 0x100
	s_barrier
	s_cbranch_scc1 .LBB0_700

.LBB0_804:
	s_and_b32 s14, s18, 3
	s_lshl_b32 s30, s14, 21
	s_mov_b64 s[14:15], s[0:1]
	s_load_dwordx2 s[14:15], s[14:15], 0xa0
	s_mov_b64 s[22:23], s[0:1]
	v_mov_b32_e32 v3, v0
	s_load_dwordx2 s[22:23], s[22:23], 0xa0
	s_and_b32 s20, s96, 3
	v_readfirstlane_b32 s21, v3
	s_ashr_i32 s31, s21, 6
	s_ashr_i32 s19, s96, 2
	s_lshl_b32 s28, s20, 21
	s_lshl_b32 s21, s31, 5
	v_bfe_u32 v2, v3, 3, 3
	s_waitcnt lgkmcnt(0)
	s_add_u32 s33, s14, s28
	v_or_b32_e32 v4, s21, v2
	v_lshlrev_b32_e32 v5, 4, v3
	s_addc_u32 s36, s15, 0
	v_lshlrev_b32_e32 v4, 7, v4
	v_and_b32_e32 v6, 48, v3
	v_and_b32_e32 v5, 0x70, v5
	s_add_u32 s26, s33, 0x51400000
	v_bitop3_b32 v34, v4, v5, v6 bitop3:0xf6
	v_or_b32_e32 v4, 8, v2
	s_addc_u32 s27, s36, 0
	s_ashr_i32 s24, s96, 4
	v_or_b32_e32 v5, s21, v4
	v_lshrrev_b32_e32 v4, 1, v4
	s_ashr_i32 s25, s24, 31
	v_xor_b32_e32 v4, v4, v3
	s_lshl_b64 s[24:25], s[24:25], 23
	v_lshlrev_b32_e32 v5, 7, v5
	v_lshlrev_b32_e32 v4, 4, v4
	s_add_u32 s22, s22, s24
	v_and_or_b32 v36, v4, s2, v5
	v_or_b32_e32 v4, 24, v2
	s_addc_u32 s23, s23, s25
	v_or_b32_e32 v5, s21, v4
	v_lshrrev_b32_e32 v4, 1, v4
	s_add_u32 s22, s22, s28
	v_xor_b32_e32 v4, v4, v3
	s_addc_u32 s23, s23, 0
	s_lshl_b32 s24, s19, 13
	v_lshlrev_b32_e32 v5, 7, v5
	v_lshlrev_b32_e32 v4, 4, v4
	v_lshl_or_b32 v2, s31, 3, v2
	s_and_b32 s24, s24, 0x6000
	v_and_or_b32 v38, v4, s2, v5
	v_lshlrev_b32_e32 v4, 7, v2
	v_lshrrev_b32_e32 v2, 1, v2
	s_add_u32 s28, s22, s24
	v_xor_b32_e32 v2, v2, v3
	s_addc_u32 s29, s23, 0
	s_lshl_b32 s22, s31, 12
	v_lshlrev_b32_e32 v2, 4, v2
	s_add_i32 s23, s22, 0
	v_and_or_b32 v2, v2, s2, v4
	v_lshl_add_u64 v[4:5], s[26:27], 0, v[34:35]
	s_mov_b32 s24, m0
	s_mov_b32 m0, s23
	s_nop 0
	global_load_lds_dwordx4 v[4:5], off
	s_mov_b32 m0, s24
	s_or_b32 s23, s22, 0x400
	v_mov_b32_e32 v37, v35
	s_add_i32 s24, s23, 0
	v_lshl_add_u64 v[6:7], s[26:27], 0, v[36:37]
	s_mov_b32 s25, m0
	s_mov_b32 m0, s24
	s_nop 0
	global_load_lds_dwordx4 v[6:7], off
	s_mov_b32 m0, s25
	s_or_b32 s24, s22, 0x800
	s_add_i32 s25, s24, 0
	v_lshl_add_u64 v[4:5], v[4:5], 0, s[4:5]
	s_mov_b32 s37, m0
	s_mov_b32 m0, s25
	s_nop 0
	global_load_lds_dwordx4 v[4:5], off
	s_mov_b32 m0, s37
	v_mov_b32_e32 v39, v35
	s_or_b32 s25, s22, 0xc00
	v_lshl_add_u64 v[4:5], s[26:27], 0, v[38:39]
	s_add_i32 s26, s25, 0
	s_mov_b32 s27, m0
	s_mov_b32 m0, s26
	s_nop 0
	global_load_lds_dwordx4 v[4:5], off
	s_mov_b32 m0, s27
	s_lshl_b32 s27, s31, 10
	v_and_b32_e32 v1, 31, v3
	v_bfe_u32 v42, v3, 5, 1
	v_lshrrev_b32_e32 v9, 1, v3
	v_bfe_u32 v10, v3, 1, 3
	v_mov_b32_e32 v3, v35
	s_add_i32 s26, s27, 0x8000
	s_add_i32 s27, s27, 0
	v_lshl_add_u64 v[2:3], s[28:29], 0, v[2:3]
	s_add_i32 s28, s27, 0x8000
	v_lshl_add_u64 v[40:41], v[2:3], 0, s[6:7]
	s_mov_b32 s29, m0
	s_mov_b32 m0, s28
	s_nop 0
	global_load_lds_dwordx4 v[40:41], off nt
	s_mov_b32 m0, s29
	s_add_u32 s28, s33, 0x51408000
	s_addc_u32 s29, s36, 0
	v_lshl_add_u64 v[4:5], s[28:29], 0, v[34:35]
	s_add_i32 s31, s22, s17
	s_mov_b32 s33, m0
	s_mov_b32 m0, s31
	s_nop 0
	global_load_lds_dwordx4 v[4:5], off
	s_mov_b32 m0, s33
	v_lshl_add_u64 v[6:7], s[28:29], 0, v[36:37]
	s_add_i32 s31, s23, s17
	s_mov_b32 s33, m0
	s_mov_b32 m0, s31
	s_nop 0
	global_load_lds_dwordx4 v[6:7], off
	s_mov_b32 m0, s33
	v_lshl_add_u64 v[4:5], v[4:5], 0, s[4:5]
	s_add_i32 s31, s24, s17
	s_mov_b32 s33, m0
	s_mov_b32 m0, s31
	s_nop 0
	global_load_lds_dwordx4 v[4:5], off
	s_mov_b32 m0, s33
	v_lshl_add_u64 v[4:5], s[28:29], 0, v[38:39]
	s_add_i32 s28, s25, s17
	s_mov_b32 s29, m0
	s_mov_b32 m0, s28
	s_nop 0
	global_load_lds_dwordx4 v[4:5], off
	s_mov_b32 m0, s29
	v_lshl_add_u64 v[2:3], v[2:3], 0, s[8:9]
	s_add_i32 s27, s27, 0x12000
	s_mov_b32 s28, m0
	s_mov_b32 m0, s27
	s_nop 0
	global_load_lds_dwordx4 v[2:3], off nt
	s_mov_b32 m0, s28
	v_bitop3_b32 v2, v42, v9, 7 bitop3:0x78
	v_lshlrev_b32_e32 v47, 4, v2
	v_bitop3_b32 v2, v42, v10, 2 bitop3:0x36
	v_lshlrev_b32_e32 v45, 4, v2
	v_bitop3_b32 v2, v42, v10, 4 bitop3:0x36
	v_or_b32_e32 v8, s21, v1
	v_lshlrev_b32_e32 v44, 4, v2
	v_bitop3_b32 v2, v42, v10, 6 bitop3:0x36
	s_add_u32 s27, s14, s30
	v_lshlrev_b32_e32 v48, 7, v8
	v_lshlrev_b32_e32 v46, 7, v1
	v_lshlrev_b32_e32 v43, 4, v2
	s_addc_u32 s28, s15, 0
	s_mov_b64 s[14:15], 0
	s_mov_b32 s30, 0
	s_mov_b32 s29, 2
	v_mov_b32_e32 v2, v35
	v_mov_b32_e32 v3, v35
	v_mov_b32_e32 v4, v35
	v_mov_b32_e32 v5, v35
	v_mov_b32_e32 v6, v35
	v_mov_b32_e32 v7, v35
	v_mov_b32_e32 v8, v35
	v_mov_b32_e32 v9, v35
	v_mov_b32_e32 v10, v35
	v_mov_b32_e32 v11, v35
	v_mov_b32_e32 v12, v35
	v_mov_b32_e32 v13, v35
	v_mov_b32_e32 v14, v35
	v_mov_b32_e32 v15, v35
	v_mov_b32_e32 v16, v35
	v_mov_b32_e32 v17, v35
	v_mov_b32_e32 v18, v35
	v_mov_b32_e32 v19, v35
	v_mov_b32_e32 v20, v35
	v_mov_b32_e32 v21, v35
	v_mov_b32_e32 v22, v35
	v_mov_b32_e32 v23, v35
	v_mov_b32_e32 v24, v35
	v_mov_b32_e32 v25, v35
	v_mov_b32_e32 v26, v35
	v_mov_b32_e32 v27, v35
	v_mov_b32_e32 v28, v35
	v_mov_b32_e32 v29, v35
	v_mov_b32_e32 v30, v35
	v_mov_b32_e32 v31, v35
	v_mov_b32_e32 v32, v35
	v_mov_b32_e32 v33, v35
.LBB0_805:
	s_mul_i32 s31, s29, 0xa000
	s_add_i32 s31, s31, 0
	s_add_u32 s38, s27, s14
	s_addc_u32 s39, s28, s15
	s_waitcnt vmcnt(5)
	s_mul_i32 s33, s30, 0xa000
	s_add_u32 s36, s38, 0x51410000
	v_lshl_add_u64 v[50:51], v[40:41], 0, s[14:15]
	s_waitcnt lgkmcnt(0)
	s_barrier
	s_addc_u32 s37, s39, 0
	s_add_i32 s40, s31, s22
	s_add_i32 s41, s31, s23
	s_add_i32 s42, s31, s24
	s_add_i32 s43, s31, s25
	s_add_i32 s31, s26, s31
	s_add_i32 s33, s33, 0
	s_add_i32 s44, s30, 1
	v_lshl_add_u64 v[52:53], v[50:51], 0, s[10:11]
	v_lshl_add_u64 v[74:75], v[50:51], 0, s[12:13]
	v_lshl_add_u64 v[50:51], s[36:37], 0, v[34:35]
	s_cmp_lg_u32 s30, 2
	s_mov_b32 s30, m0
	s_mov_b32 m0, s40
	s_nop 0
	global_load_lds_dwordx4 v[50:51], off
	s_mov_b32 m0, s30
	v_lshl_add_u64 v[54:55], s[36:37], 0, v[36:37]
	s_mov_b32 s30, m0
	s_mov_b32 m0, s41
	s_nop 0
	global_load_lds_dwordx4 v[54:55], off
	s_mov_b32 m0, s30
	v_lshl_add_u64 v[50:51], v[50:51], 0, s[4:5]
	s_mov_b32 s30, m0
	s_mov_b32 m0, s42
	s_nop 0
	global_load_lds_dwordx4 v[50:51], off
	s_mov_b32 m0, s30
	v_lshl_add_u64 v[56:57], s[36:37], 0, v[38:39]
	v_add_u32_e32 v49, s33, v48
	s_mov_b32 s30, m0
	s_mov_b32 m0, s43
	s_nop 0
	global_load_lds_dwordx4 v[56:57], off
	s_mov_b32 m0, s30
	v_add_u32_e32 v62, s33, v46
	v_add_u32_e32 v58, v49, v47
	s_mov_b32 s30, m0
	s_mov_b32 m0, s31
	s_nop 0
	global_load_lds_dwordx4 v[52:53], off nt
	s_mov_b32 m0, s30
	v_add_u32_e32 v59, v62, v47
	ds_read_b128 v[50:53], v58
	ds_read_b128 v[54:57], v59 offset:32768
	v_add_u32_e32 v60, v49, v45
	s_waitcnt lgkmcnt(0)
	v_mfma_f32_32x32x16_bf16 v[2:17], v[50:53], v[54:57], v[2:17]
	ds_read_b128 v[54:57], v59 offset:36864
	ds_read_b128 v[58:61], v60
	v_add_u32_e32 v63, v62, v45
	v_add_u32_e32 v64, v49, v44
	v_add_u32_e32 v65, v62, v44
	v_add_u32_e32 v70, v62, v43
	v_add_u32_e32 v49, v49, v43
	s_cselect_b32 s33, s44, 0
	s_waitcnt lgkmcnt(0)
	v_mfma_f32_32x32x16_bf16 v[18:33], v[50:53], v[54:57], v[18:33]
	ds_read_b128 v[50:53], v63 offset:32768
	ds_read_b128 v[54:57], v63 offset:36864
	s_add_i32 s30, s29, 1
	s_cmp_lg_u32 s29, 2
	s_cselect_b32 s36, s30, 0
	s_mul_i32 s30, s36, 0xa000
	s_add_i32 s37, s30, 0
	s_mul_i32 s29, s33, 0xa000
	s_waitcnt lgkmcnt(0)
	v_mfma_f32_32x32x16_bf16 v[2:17], v[58:61], v[50:53], v[2:17]
	ds_read_b128 v[50:53], v64
	s_add_u32 s30, s38, 0x51418000
	s_addc_u32 s31, s39, 0
	s_add_i32 s29, s29, 0
	s_add_i32 s38, s37, s22
	v_add_u32_e32 v76, s29, v46
	s_add_i32 s39, s37, s23
	v_mfma_f32_32x32x16_bf16 v[18:33], v[58:61], v[54:57], v[18:33]
	ds_read_b128 v[54:57], v65 offset:32768
	ds_read_b128 v[58:61], v65 offset:36864
	ds_read_b128 v[62:65], v49
	ds_read_b128 v[66:69], v70 offset:32768
	ds_read_b128 v[70:73], v70 offset:36864
	s_waitcnt vmcnt(5)
	s_waitcnt lgkmcnt(0)
	s_barrier
	v_add_u32_e32 v49, s29, v48
	s_add_i32 s40, s37, s24
	s_add_i32 s41, s37, s25
	s_add_i32 s37, s26, s37
	s_waitcnt lgkmcnt(0)
	v_mfma_f32_32x32x16_bf16 v[2:17], v[50:53], v[54:57], v[2:17]
	v_lshl_add_u64 v[54:55], s[30:31], 0, v[38:39]
	v_add_u32_e32 v56, v49, v47
	v_mfma_f32_32x32x16_bf16 v[18:33], v[50:53], v[58:61], v[18:33]
	v_lshl_add_u64 v[50:51], s[30:31], 0, v[34:35]
	s_mov_b32 s29, m0
	s_mov_b32 m0, s38
	s_nop 0
	global_load_lds_dwordx4 v[50:51], off
	s_mov_b32 m0, s29
	v_lshl_add_u64 v[52:53], s[30:31], 0, v[36:37]
	s_mov_b32 s29, m0
	s_mov_b32 m0, s39
	s_nop 0
	global_load_lds_dwordx4 v[52:53], off
	s_mov_b32 m0, s29
	v_lshl_add_u64 v[50:51], v[50:51], 0, s[4:5]
	s_mov_b32 s29, m0
	s_mov_b32 m0, s40
	s_nop 0
	global_load_lds_dwordx4 v[50:51], off
	s_mov_b32 m0, s29
	v_add_u32_e32 v58, v76, v47
	v_mfma_f32_32x32x16_bf16 v[2:17], v[62:65], v[66:69], v[2:17]
	s_mov_b32 s29, m0
	s_mov_b32 m0, s41
	s_nop 0
	global_load_lds_dwordx4 v[54:55], off
	s_mov_b32 m0, s29
	v_add_u32_e32 v59, v49, v45
	s_mov_b32 s29, m0
	s_mov_b32 m0, s37
	s_nop 0
	global_load_lds_dwordx4 v[74:75], off nt
	s_mov_b32 m0, s29
	ds_read_b128 v[50:53], v56
	ds_read_b128 v[54:57], v58 offset:32768
	s_add_i32 s29, s33, 1
	s_cmp_lg_u32 s33, 2
	s_cselect_b32 s30, s29, 0
	v_mfma_f32_32x32x16_bf16 v[18:33], v[62:65], v[70:73], v[18:33]
	v_add_u32_e32 v62, v76, v44
	s_add_i32 s29, s36, 1
	s_cmp_lg_u32 s36, 2
	s_cselect_b32 s29, s29, 0
	s_add_u32 s14, s14, 0x10000
	s_addc_u32 s15, s15, 0
	s_cmp_eq_u32 s14, 0x1f0000
	s_waitcnt lgkmcnt(0)
	v_mfma_f32_32x32x16_bf16 v[2:17], v[50:53], v[54:57], v[2:17]
	ds_read_b128 v[54:57], v58 offset:36864
	ds_read_b128 v[58:61], v59
	s_waitcnt lgkmcnt(0)
	v_mfma_f32_32x32x16_bf16 v[18:33], v[50:53], v[54:57], v[18:33]
	v_add_u32_e32 v54, v76, v45
	ds_read_b128 v[50:53], v54 offset:32768
	ds_read_b128 v[54:57], v54 offset:36864
	s_waitcnt lgkmcnt(0)
	v_mfma_f32_32x32x16_bf16 v[2:17], v[58:61], v[50:53], v[2:17]
	v_add_u32_e32 v50, v49, v44
	v_add_u32_e32 v49, v49, v43
	v_mfma_f32_32x32x16_bf16 v[18:33], v[58:61], v[54:57], v[18:33]
	ds_read_b128 v[50:53], v50
	ds_read_b128 v[54:57], v62 offset:32768
	s_waitcnt lgkmcnt(0)
	v_mfma_f32_32x32x16_bf16 v[2:17], v[50:53], v[54:57], v[2:17]
	ds_read_b128 v[54:57], v62 offset:36864
	ds_read_b128 v[58:61], v49
	v_add_u32_e32 v49, v76, v43
	s_waitcnt lgkmcnt(0)
	v_mfma_f32_32x32x16_bf16 v[18:33], v[50:53], v[54:57], v[18:33]
	ds_read_b128 v[50:53], v49 offset:32768
	ds_read_b128 v[54:57], v49 offset:36864
	s_waitcnt lgkmcnt(0)
	v_mfma_f32_32x32x16_bf16 v[2:17], v[58:61], v[50:53], v[2:17]
	v_mfma_f32_32x32x16_bf16 v[18:33], v[58:61], v[54:57], v[18:33]
	s_cbranch_scc0 .LBB0_805
	s_mul_i32 s14, s30, 0xa000
	s_add_i32 s14, s14, 0
	s_waitcnt vmcnt(5)
	v_add_u32_e32 v34, s14, v48
	s_waitcnt lgkmcnt(0)
	s_barrier
	v_add_u32_e32 v36, v34, v47
	ds_read_b128 v[36:39], v36
	v_add_u32_e32 v40, s14, v46
	v_add_u32_e32 v41, v40, v47
	ds_read_b128 v[50:53], v41 offset:32768
	s_lshl_b32 s14, s20, 8
	s_ashr_i32 s15, s21, 31
	s_add_u32 s20, s21, s14
	s_waitcnt lgkmcnt(0)
	v_mfma_f32_32x32x16_bf16 v[2:17], v[36:39], v[50:53], v[2:17]
	ds_read_b128 v[50:53], v41 offset:36864
	v_add_u32_e32 v41, v34, v45
	ds_read_b128 v[54:57], v41
	v_add_u32_e32 v41, v40, v45
	s_addc_u32 s21, s15, 0
	s_lshl_b32 s14, s19, 6
	s_ashr_i32 s15, s14, 31
	s_waitcnt lgkmcnt(0)
	v_mfma_f32_32x32x16_bf16 v[18:33], v[36:39], v[50:53], v[18:33]
	ds_read_b128 v[36:39], v41 offset:32768
	ds_read_b128 v[50:53], v41 offset:36864
	v_add_u32_e32 v41, v40, v44
	s_lshl_b64 s[14:15], s[14:15], 2
	s_add_u32 s14, s3, s14
	s_addc_u32 s15, s16, s15
	s_add_i32 s96, s96, s93
	s_add_i32 s18, s18, s93
	s_waitcnt lgkmcnt(0)
	v_mfma_f32_32x32x16_bf16 v[2:17], v[54:57], v[36:39], v[2:17]
	v_add_u32_e32 v36, v34, v44
	ds_read_b128 v[36:39], v36
	v_add_u32_e32 v34, v34, v43
	s_cmpk_gt_i32 s96, 0xff
	v_mfma_f32_32x32x16_bf16 v[18:33], v[54:57], v[50:53], v[18:33]
	ds_read_b128 v[50:53], v41 offset:32768
	ds_read_b128 v[54:57], v34
	v_add_u32_e32 v34, v40, v43
	v_add_u32_e32 v40, 0, v46
	s_waitcnt lgkmcnt(0)
	v_mfma_f32_32x32x16_bf16 v[2:17], v[36:39], v[50:53], v[2:17]
	ds_read_b128 v[50:53], v41 offset:36864
	v_add_u32_e32 v41, v40, v47
	s_waitcnt lgkmcnt(0)
	v_mfma_f32_32x32x16_bf16 v[18:33], v[36:39], v[50:53], v[18:33]
	ds_read_b128 v[36:39], v34 offset:32768
	ds_read_b128 v[50:53], v34 offset:36864
	s_waitcnt vmcnt(0)
	v_add_u32_e32 v34, 0, v48
	s_waitcnt lgkmcnt(0)
	s_barrier
	s_waitcnt lgkmcnt(0)
	v_mfma_f32_32x32x16_bf16 v[2:17], v[54:57], v[36:39], v[2:17]
	v_add_u32_e32 v36, v34, v47
	ds_read_b128 v[36:39], v36
	ds_read_b128 v[46:49], v41 offset:32768
	v_mfma_f32_32x32x16_bf16 v[18:33], v[54:57], v[50:53], v[18:33]
	s_waitcnt lgkmcnt(0)
	v_mfma_f32_32x32x16_bf16 v[2:17], v[36:39], v[46:49], v[2:17]
	ds_read_b128 v[46:49], v41 offset:36864
	v_add_u32_e32 v41, v34, v45
	ds_read_b128 v[50:53], v41
	v_add_u32_e32 v41, v40, v45
	s_waitcnt lgkmcnt(0)
	v_mfma_f32_32x32x16_bf16 v[18:33], v[36:39], v[46:49], v[18:33]
	ds_read_b128 v[36:39], v41 offset:32768
	ds_read_b128 v[46:49], v41 offset:36864
	v_add_u32_e32 v41, v40, v44
	s_waitcnt lgkmcnt(0)
	v_mfma_f32_32x32x16_bf16 v[2:17], v[50:53], v[36:39], v[2:17]
	v_add_u32_e32 v36, v34, v44
	ds_read_b128 v[36:39], v36
	v_add_u32_e32 v34, v34, v43
	v_mfma_f32_32x32x16_bf16 v[18:33], v[50:53], v[46:49], v[18:33]
	ds_read_b128 v[44:47], v41 offset:32768
	s_waitcnt lgkmcnt(0)
	v_mfma_f32_32x32x16_bf16 v[2:17], v[36:39], v[44:47], v[2:17]
	ds_read_b128 v[44:47], v41 offset:36864
	ds_read_b128 v[48:51], v34
	v_add_u32_e32 v34, v40, v43
	ds_read_b128 v[52:55], v34 offset:32768
	ds_read_b128 v[56:59], v34 offset:36864
	v_lshlrev_b32_e32 v34, 2, v1
	s_waitcnt lgkmcnt(0)
	v_mfma_f32_32x32x16_bf16 v[18:33], v[36:39], v[44:47], v[18:33]
	v_lshl_or_b32 v38, v42, 2, s20
	v_mov_b32_e32 v39, s21
	v_lshl_add_u64 v[36:37], s[14:15], 0, v[34:35]
	v_lshlrev_b64 v[40:41], 14, v[38:39]
	v_lshl_add_u64 v[40:41], v[36:37], 0, v[40:41]
	v_mfma_f32_32x32x16_bf16 v[2:17], v[48:51], v[52:55], v[2:17]
	v_mfma_f32_32x32x16_bf16 v[18:33], v[48:51], v[56:59], v[18:33]
	s_nop 10
	global_store_dword v[40:41], v2, off
	v_or_b32_e32 v2, 2, v38
	global_store_dword v[40:41], v18, off offset:128
	v_or_b32_e32 v40, 1, v38
	v_mov_b32_e32 v41, s21
	v_lshlrev_b64 v[40:41], 14, v[40:41]
	v_lshl_add_u64 v[40:41], v[36:37], 0, v[40:41]
	global_store_dword v[40:41], v3, off
	global_store_dword v[40:41], v19, off offset:128
	v_mov_b32_e32 v3, s21
	v_lshlrev_b64 v[2:3], 14, v[2:3]
	v_lshl_add_u64 v[2:3], v[36:37], 0, v[2:3]
	global_store_dword v[2:3], v4, off
	global_store_dword v[2:3], v20, off offset:128
	v_or_b32_e32 v2, 3, v38
	v_mov_b32_e32 v3, s21
	v_lshlrev_b64 v[2:3], 14, v[2:3]
	v_lshl_add_u64 v[2:3], v[36:37], 0, v[2:3]
	global_store_dword v[2:3], v5, off
	global_store_dword v[2:3], v21, off offset:128
	v_or_b32_e32 v2, 8, v38
	v_mov_b32_e32 v3, s21
	v_lshlrev_b64 v[2:3], 14, v[2:3]
	v_lshl_add_u64 v[2:3], v[36:37], 0, v[2:3]
	global_store_dword v[2:3], v6, off
	global_store_dword v[2:3], v22, off offset:128
	v_or_b32_e32 v2, 9, v38
	v_mov_b32_e32 v3, s21
	v_lshlrev_b64 v[2:3], 14, v[2:3]
	v_lshl_add_u64 v[2:3], v[36:37], 0, v[2:3]
	global_store_dword v[2:3], v7, off
	global_store_dword v[2:3], v23, off offset:128
	v_or_b32_e32 v2, 10, v38
	v_mov_b32_e32 v3, s21
	v_lshlrev_b64 v[2:3], 14, v[2:3]
	v_lshl_add_u64 v[2:3], v[36:37], 0, v[2:3]
	global_store_dword v[2:3], v8, off
	global_store_dword v[2:3], v24, off offset:128
	v_or_b32_e32 v2, 11, v38
	v_mov_b32_e32 v3, s21
	v_lshlrev_b64 v[2:3], 14, v[2:3]
	v_lshl_add_u64 v[2:3], v[36:37], 0, v[2:3]
	global_store_dword v[2:3], v9, off
	global_store_dword v[2:3], v25, off offset:128
	v_or_b32_e32 v2, 16, v38
	v_mov_b32_e32 v3, s21
	v_lshlrev_b64 v[2:3], 14, v[2:3]
	v_lshl_add_u64 v[2:3], v[36:37], 0, v[2:3]
	global_store_dword v[2:3], v10, off
	global_store_dword v[2:3], v26, off offset:128
	v_or_b32_e32 v2, 17, v38
	v_mov_b32_e32 v3, s21
	v_lshlrev_b64 v[2:3], 14, v[2:3]
	v_lshl_add_u64 v[2:3], v[36:37], 0, v[2:3]
	global_store_dword v[2:3], v11, off
	global_store_dword v[2:3], v27, off offset:128
	v_or_b32_e32 v2, 18, v38
	v_mov_b32_e32 v3, s21
	v_lshlrev_b64 v[2:3], 14, v[2:3]
	v_lshl_add_u64 v[2:3], v[36:37], 0, v[2:3]
	global_store_dword v[2:3], v12, off
	global_store_dword v[2:3], v28, off offset:128
	v_or_b32_e32 v2, 19, v38
	v_mov_b32_e32 v3, s21
	v_lshlrev_b64 v[2:3], 14, v[2:3]
	v_lshl_add_u64 v[2:3], v[36:37], 0, v[2:3]
	global_store_dword v[2:3], v13, off
	global_store_dword v[2:3], v29, off offset:128
	v_or_b32_e32 v2, 24, v38
	v_mov_b32_e32 v3, s21
	v_lshlrev_b64 v[2:3], 14, v[2:3]
	v_lshl_add_u64 v[2:3], v[36:37], 0, v[2:3]
	global_store_dword v[2:3], v14, off
	global_store_dword v[2:3], v30, off offset:128
	v_or_b32_e32 v2, 25, v38
	v_mov_b32_e32 v3, s21
	v_lshlrev_b64 v[2:3], 14, v[2:3]
	v_lshl_add_u64 v[2:3], v[36:37], 0, v[2:3]
	global_store_dword v[2:3], v15, off
	global_store_dword v[2:3], v31, off offset:128
	v_or_b32_e32 v2, 26, v38
	v_mov_b32_e32 v3, s21
	v_lshlrev_b64 v[2:3], 14, v[2:3]
	v_lshl_add_u64 v[2:3], v[36:37], 0, v[2:3]
	v_or_b32_e32 v38, 27, v38
	global_store_dword v[2:3], v16, off
	global_store_dword v[2:3], v32, off offset:128
	v_lshlrev_b64 v[2:3], 14, v[38:39]
	v_lshl_add_u64 v[2:3], v[36:37], 0, v[2:3]
	global_store_dword v[2:3], v17, off
	global_store_dword v[2:3], v33, off offset:128
	s_waitcnt lgkmcnt(0)
	s_waitcnt vmcnt(0)
	s_barrier
	s_cbranch_scc0 .LBB0_804
